# cumulative: gdn RAW staging unrolled, P0 row-loop hoists + next-row prefetch, P1 epilogue fast path, P4a gemm1 prologue loads batched, P3 output block batched
# speedup vs baseline: 1.1479x; 1.0301x over previous
; __device__ __forceinline__ float wsum(float v) { v = dpp_row_sum16(v); v += __shfl_xor(v, 16); v += __shfl_xor(v, 32); return v; }
; __device__ __forceinline__ float sigmoidf_(float x) { return __builtin_amdgcn_rcpf(1.f + __expf(-x)); }
; __device__ __forceinline__ void phase0(const Params& p, char* smem) {
;     ...
;   for (int it = blockIdx.x; it < NT / 4; it += gridDim.x) {
;     const int row = it * 4 + w;
;     const float* xr = xrow(p, row);
;     float4 xv[4]; float ss = 0.f;
; #pragma unroll
;     for (int i = 0; i < 4; i++) { xv[i] = *(const float4*)(xr + i * 256 + lane * 4); ss += xv[i].x * xv[i].x + xv[i].y * xv[i].y + xv[i].z * xv[i].z + xv[i].w * xv[i].w; }
;     ss = wsum(ss);
;     const float rs = rsqrtf(ss * (1.f / 1024.f) + EPSF);
;     float d8[8];
; #pragma unroll
;     for (int j = 0; j < 8; j++) d8[j] = 0.f;
; #pragma unroll
;     for (int i = 0; i < 4; i++) {
;       const int k = i * 256 + lane * 4;
;       float4 g = *(const float4*)(p.g_mix + k);
;       float hv[4] = {xv[i].x * rs * g.x, xv[i].y * rs * g.y, xv[i].z * rs * g.z, xv[i].w * rs * g.w};
;       *(uint2*)(H + (size_t)row * 1024 + k) = make_uint2(pack2(hv[0], hv[1]), pack2(hv[2], hv[3]));
; #pragma unroll
;       for (int q = 0; q < 4; q++) {
;         float4 wa = *(const float4*)&w8[(k + q) * 8], wb = *(const float4*)&w8[(k + q) * 8 + 4];
;         d8[0] += hv[q] * wa.x; d8[1] += hv[q] * wa.y; d8[2] += hv[q] * wa.z; d8[3] += hv[q] * wa.w;
;         d8[4] += hv[q] * wb.x; d8[5] += hv[q] * wb.y; d8[6] += hv[q] * wb.z; d8[7] += hv[q] * wb.w;
;       }
;     }
; #pragma unroll
;     for (int j = 0; j < 8; j++) d8[j] = wsum(d8[j]);
;     if (lane < 4) {
;       float bb = lane == 0 ? d8[0] : lane == 1 ? d8[1] : lane == 2 ? d8[2] : d8[3];
;       float ab = lane == 0 ? d8[4] : lane == 1 ? d8[5] : lane == 2 ? d8[6] : d8[7];
;       BETA[row * 4 + lane] = sigmoidf_(bb);
;       float z = ab + p.dt_bias[lane];
;       float sp = z > 20.f ? z : log1pf(expf(z));
;       GLOG[row * 4 + lane] = -expf(p.a_log[lane]) * sp;
;     }
;     if (lane == 0) { SSQ1[row] = 0.f; SSQ3[row] = 0.f; }
;   }
.LBB0_97:
	s_or_b64 exec, exec, s[0:1]
	s_add_u32 s38, s80, 0x1700000
	s_addc_u32 s39, s81, 0
	s_add_u32 s0, s80, 0x3800000
	s_addc_u32 s1, s81, 0
	v_writelane_b32 v254, s0, 36
	v_and_b32_e32 v231, 63, v237
	v_lshrrev_b32_e32 v1, 6, v237
	v_writelane_b32 v254, s1, 37
	s_add_u32 s0, s80, 0x3842000
	s_addc_u32 s1, s81, 0
	s_add_u32 s94, s80, 0x3b94000
	s_addc_u32 s95, s81, 0
	s_add_u32 s92, s80, 0x3ba4800
	s_addc_u32 s93, s81, 0
	v_lshlrev_b32_e32 v2, 4, v231
	v_writelane_b32 v254, s0, 38
	s_cmpk_lt_i32 s96, 0x1080
	v_accvgpr_write_b32 a134, v2
	v_lshl_add_u32 v2, s96, 2, v1
	v_writelane_b32 v254, s1, 39
	s_cselect_b64 s[10:11], -1, 0
	s_cmpk_gt_i32 s96, 0x107f
	v_accvgpr_write_b32 a129, v1
	v_accvgpr_write_b32 a136, v2
	s_waitcnt lgkmcnt(0)
	s_barrier
	s_cbranch_scc1 .LBB0_106
	v_mbcnt_lo_u32_b32 v1, -1, 0
	v_mbcnt_hi_u32_b32 v2, -1, v1
	v_and_b32_e32 v3, 64, v2
	v_xor_b32_e32 v1, 16, v2
	v_add_u32_e32 v3, 64, v3
	v_cmp_lt_i32_e32 vcc, v1, v3
	v_xor_b32_e32 v4, 32, v2
	v_readlane_b32 s12, v254, 3
	v_cndmask_b32_e32 v1, v2, v1, vcc
	v_cmp_lt_i32_e32 vcc, v4, v3
	v_mov_b32_e32 v143, 0
	v_readlane_b32 s13, v254, 4
	v_cndmask_b32_e32 v2, v2, v4, vcc
	v_lshlrev_b32_e32 v134, 2, v2
	v_lshlrev_b32_e32 v126, 7, v231
	v_accvgpr_read_b32 v2, a134
	v_mov_b32_e32 v3, v143
	s_mov_b64 s[8:9], s[12:13]
	v_lshl_add_u64 v[144:145], s[8:9], 0, v[2:3]
	ds_read_b128 v[2:5], v126
	ds_read_b128 v[6:9], v126 offset:16
	ds_read_b128 v[10:13], v126 offset:32
	ds_read_b128 v[14:17], v126 offset:48
	ds_read_b128 v[18:21], v126 offset:64
	ds_read_b128 v[22:25], v126 offset:80
	ds_read_b128 v[26:29], v126 offset:96
	ds_read_b128 v[30:33], v126 offset:112
	ds_read_b128 v[34:37], v126 offset:8192
	ds_read_b128 v[38:41], v126 offset:8208
	ds_read_b128 v[42:45], v126 offset:8224
	ds_read_b128 v[46:49], v126 offset:8240
	ds_read_b128 v[50:53], v126 offset:8256
	ds_read_b128 v[54:57], v126 offset:8272
	ds_read_b128 v[58:61], v126 offset:8288
	ds_read_b128 v[62:65], v126 offset:8304
	ds_read_b128 v[66:69], v126 offset:16384
	ds_read_b128 v[70:73], v126 offset:16400
	ds_read_b128 v[74:77], v126 offset:16416
	ds_read_b128 v[78:81], v126 offset:16432
	ds_read_b128 v[82:85], v126 offset:16448
	ds_read_b128 v[86:89], v126 offset:16464
	ds_read_b128 v[90:93], v126 offset:16480
	ds_read_b128 v[94:97], v126 offset:16496
	ds_read_b128 v[98:101], v126 offset:24576
	ds_read_b128 v[102:105], v126 offset:24592
	ds_read_b128 v[106:109], v126 offset:24608
	ds_read_b128 v[110:113], v126 offset:24624
	ds_read_b128 v[114:117], v126 offset:24640
	ds_read_b128 v[118:121], v126 offset:24656
	ds_read_b128 v[122:125], v126 offset:24672
	ds_read_b128 v[126:129], v126 offset:24688
	v_readlane_b32 s14, v254, 5
	v_readlane_b32 s15, v254, 6
	v_readlane_b32 s16, v254, 7
	v_readlane_b32 s17, v254, 8
	v_readlane_b32 s18, v254, 9
	v_readlane_b32 s19, v254, 10
	v_readlane_b32 s20, v254, 11
	v_readlane_b32 s21, v254, 12
	v_lshlrev_b32_e32 v130, 3, v231
	v_mov_b32_e32 v131, v143
	v_readlane_b32 s22, v254, 13
	v_readlane_b32 s23, v254, 14
	v_readlane_b32 s24, v254, 15
	v_readlane_b32 s25, v254, 16
	s_mov_b64 s[12:13], s[16:17]
	v_lshl_add_u64 v[150:151], s[38:39], 0, v[130:131]
	v_accvgpr_read_b32 v130, a129
	v_lshlrev_b32_e32 v142, 2, v231
	v_readlane_b32 s26, v254, 17
	v_readlane_b32 s27, v254, 18
	s_mov_b64 s[14:15], s[18:19]
	s_mov_b64 s[16:17], s[20:21]
	s_mov_b64 s[18:19], s[22:23]
	s_mov_b64 s[20:21], s[24:25]
	s_lshl_b32 s8, s96, 4
	v_lshlrev_b32_e32 v130, 2, v130
	v_lshlrev_b32_e32 v1, 2, v1
	v_cmp_gt_u32_e32 vcc, 4, v231
	v_cmp_eq_u32_e64 s[0:1], 0, v231
	v_cmp_eq_u32_e64 s[4:5], 1, v231
	v_cmp_eq_u32_e64 s[6:7], 2, v231
	v_lshl_add_u64 v[146:147], s[16:17], 0, v[142:143]
	v_lshl_add_u64 v[148:149], s[14:15], 0, v[142:143]
	v_add3_u32 v152, s8, v130, v231
	s_lshl_b32 s16, s82, 4
	s_lshl_b32 s17, s82, 2
	s_movk_i32 s18, 0x4000
	v_mov_b32_e32 v135, s43
	v_mov_b32_e32 v136, s41
	v_mov_b32_e32 v137, s42
	v_mov_b32_e32 v138, s40
	v_lshlrev_b32_e32 v142, 2, v142
	v_mov_b32_e32 v139, 0x358637bd
	s_mov_b32 s19, 0x800000
	s_mov_b32 s20, 0x41a00000
	s_mov_b32 s21, 0x3fb8aa3b
	s_mov_b32 s22, 0xc2ce8ed0
	s_mov_b32 s23, 0x42b17218
	s_mov_b32 s24, 0x7f800000
	s_mov_b32 s25, 0x3f2aaaab
	v_mov_b32_e32 v141, 0x3ecc95a3
	s_mov_b32 s26, 0x3f317218
	s_mov_b32 s27, 0x33800000
	v_mov_b32_e32 v162, 0x7f800000
	v_mov_b32_e32 v154, 0x3f317218
	v_accvgpr_read_b32 v156, a136
	s_mov_b32 s28, s96
	global_load_dwordx4 a[212:215], v[144:145], off
	global_load_dwordx4 a[216:219], v[144:145], off offset:1024
	global_load_dwordx4 a[220:223], v[144:145], off offset:2048
	global_load_dwordx4 a[224:227], v[144:145], off offset:3072
	v_cmp_gt_u32_e32 vcc, 4, v231
	s_nop 1
	s_and_saveexec_b64 s[8:9], vcc
	global_load_dword a228, v[146:147], off
	global_load_dword a229, v[148:149], off
	s_mov_b64 exec, s[8:9]
	v_add_u32_e32 v180, 0xffffc000, v156
	v_ashrrev_i32_e32 v181, 31, v156
	v_cmp_gt_i32_e64 s[8:9], s18, v156
	s_nop 1
	v_cndmask_b32_e64 v181, 0, v181, s[8:9]
	v_cndmask_b32_e64 v180, v180, v156, s[8:9]
	v_cndmask_b32_e64 v183, v135, v136, s[8:9]
	v_cndmask_b32_e64 v182, v137, v138, s[8:9]
	v_lshlrev_b64 v[180:181], 12, v[180:181]
	v_lshl_add_u64 v[180:181], v[182:183], 0, v[180:181]
	v_lshl_add_u64 v[180:181], v[180:181], 0, v[142:143]
	global_load_dwordx4 a[196:199], v[180:181], off
	global_load_dwordx4 a[200:203], v[180:181], off offset:1024
	global_load_dwordx4 a[204:207], v[180:181], off offset:2048
	global_load_dwordx4 a[208:211], v[180:181], off offset:3072
	s_waitcnt vmcnt(0)
	s_branch .LBB0_100

; __device__ __forceinline__ float wsum(float v) { v = dpp_row_sum16(v); v += __shfl_xor(v, 16); v += __shfl_xor(v, 32); return v; }
; __device__ __forceinline__ void phase0(const Params& p, char* smem) {
;     ...
;     const int row = it * 4 + w;
;     const float* xr = xrow(p, row);
;     float4 xv[4]; float ss = 0.f;
; #pragma unroll
;     for (int i = 0; i < 4; i++) { xv[i] = *(const float4*)(xr + i * 256 + lane * 4); ss += xv[i].x * xv[i].x + xv[i].y * xv[i].y + xv[i].z * xv[i].z + xv[i].w * xv[i].w; }
;     ss = wsum(ss);
;     const float rs = rsqrtf(ss * (1.f / 1024.f) + EPSF);
;     float d8[8];
; #pragma unroll
;     for (int j = 0; j < 8; j++) d8[j] = 0.f;
; #pragma unroll
;     for (int i = 0; i < 4; i++) {
;       const int k = i * 256 + lane * 4;
;       float4 g = *(const float4*)(p.g_mix + k);
;       float hv[4] = {xv[i].x * rs * g.x, xv[i].y * rs * g.y, xv[i].z * rs * g.z, xv[i].w * rs * g.w};
;       *(uint2*)(H + (size_t)row * 1024 + k) = make_uint2(pack2(hv[0], hv[1]), pack2(hv[2], hv[3]));
; #pragma unroll
;       for (int q = 0; q < 4; q++) {
;         float4 wa = *(const float4*)&w8[(k + q) * 8], wb = *(const float4*)&w8[(k + q) * 8 + 4];
;         d8[0] += hv[q] * wa.x; d8[1] += hv[q] * wa.y; d8[2] += hv[q] * wa.z; d8[3] += hv[q] * wa.w;
;         d8[4] += hv[q] * wb.x; d8[5] += hv[q] * wb.y; d8[6] += hv[q] * wb.z; d8[7] += hv[q] * wb.w;
;       }
.LBB0_100:
	v_ashrrev_i32_e32 v157, 31, v156
	s_waitcnt vmcnt(4) lgkmcnt(0)
	v_accvgpr_read_b32 v164, a196
	v_accvgpr_read_b32 v165, a197
	v_accvgpr_read_b32 v166, a198
	v_accvgpr_read_b32 v167, a199
	v_accvgpr_read_b32 v168, a200
	v_accvgpr_read_b32 v169, a201
	v_accvgpr_read_b32 v170, a202
	v_accvgpr_read_b32 v171, a203
	v_accvgpr_read_b32 v172, a204
	v_accvgpr_read_b32 v173, a205
	v_accvgpr_read_b32 v174, a206
	v_accvgpr_read_b32 v175, a207
	v_accvgpr_read_b32 v130, a208
	v_accvgpr_read_b32 v131, a209
	v_accvgpr_read_b32 v132, a210
	v_accvgpr_read_b32 v133, a211
	v_accvgpr_read_b32 v176, a212
	v_accvgpr_read_b32 v177, a213
	v_accvgpr_read_b32 v178, a214
	v_accvgpr_read_b32 v179, a215
	s_add_i32 s12, s28, s82
	s_cmpk_lt_i32 s12, 0x1080
	s_cbranch_scc0 .Lp0_nopf
	v_add_u32_e32 v184, s17, v156
	v_add_u32_e32 v180, 0xffffc000, v184
	v_ashrrev_i32_e32 v181, 31, v184
	v_cmp_gt_i32_e64 s[8:9], s18, v184
	s_nop 1
	v_cndmask_b32_e64 v181, 0, v181, s[8:9]
	v_cndmask_b32_e64 v180, v180, v184, s[8:9]
	v_cndmask_b32_e64 v183, v135, v136, s[8:9]
	v_cndmask_b32_e64 v182, v137, v138, s[8:9]
	v_lshlrev_b64 v[180:181], 12, v[180:181]
	v_lshl_add_u64 v[180:181], v[182:183], 0, v[180:181]
	v_lshl_add_u64 v[180:181], v[180:181], 0, v[142:143]
	global_load_dwordx4 a[196:199], v[180:181], off
	global_load_dwordx4 a[200:203], v[180:181], off offset:1024
	global_load_dwordx4 a[204:207], v[180:181], off offset:2048
	global_load_dwordx4 a[208:211], v[180:181], off offset:3072
.Lp0_nopf:
	v_mov_b32_e32 v182, v165
	v_mov_b32_e32 v183, v169
	v_mov_b32_e32 v180, v164
	v_mov_b32_e32 v181, v168
	v_mov_b32_e32 v190, v173
	v_mov_b32_e32 v191, v131
	v_pk_mul_f32 v[182:183], v[182:183], v[182:183]
	v_mov_b32_e32 v158, v166
	v_mov_b32_e32 v159, v170
	v_mov_b32_e32 v188, v172
	v_mov_b32_e32 v189, v130
	v_pk_mul_f32 v[190:191], v[190:191], v[190:191]
	v_pk_fma_f32 v[180:181], v[180:181], v[180:181], v[182:183]
	s_waitcnt lgkmcnt(2)
	v_mov_b32_e32 v160, v167
	s_waitcnt lgkmcnt(1)
	v_mov_b32_e32 v161, v171
	v_mov_b32_e32 v184, v174
	v_mov_b32_e32 v185, v132
	v_pk_fma_f32 v[182:183], v[188:189], v[188:189], v[190:191]
	v_pk_fma_f32 v[158:159], v[158:159], v[158:159], v[180:181]
	v_mov_b32_e32 v186, v175
	v_mov_b32_e32 v187, v133
	v_pk_fma_f32 v[180:181], v[184:185], v[184:185], v[182:183]
	v_pk_fma_f32 v[158:159], v[160:161], v[160:161], v[158:159]
	v_pk_fma_f32 v[160:161], v[186:187], v[186:187], v[180:181]
	v_add_f32_e32 v153, v158, v159
	v_add_f32_e32 v153, v153, v160
	v_add_f32_e32 v153, v153, v161
	v_lshlrev_b64 v[158:159], 11, v[156:157]
	v_lshl_add_u64 v[158:159], v[150:151], 0, v[158:159]
	v_add_f32_dpp v153, v153, v153 quad_perm:[1,0,3,2] row_mask:0xf bank_mask:0xf bound_ctrl:1
	s_nop 1
	v_add_f32_dpp v153, v153, v153 quad_perm:[2,3,0,1] row_mask:0xf bank_mask:0xf bound_ctrl:1
	s_nop 1
	v_add_f32_dpp v153, v153, v153 row_half_mirror row_mask:0xf bank_mask:0xf bound_ctrl:1
	s_nop 1
	v_add_f32_dpp v153, v153, v153 row_mirror row_mask:0xf bank_mask:0xf bound_ctrl:1
	ds_bpermute_b32 v155, v1, v153
	s_waitcnt lgkmcnt(0)
	v_add_f32_e32 v153, v153, v155
	ds_bpermute_b32 v155, v134, v153
	s_waitcnt lgkmcnt(0)
	v_add_f32_e32 v153, v153, v155
	v_fmamk_f32 v153, v153, 0x3a800000, v139
	v_mul_f32_e32 v155, 0x4b800000, v153
	v_cmp_gt_f32_e64 s[8:9], s19, v153
	s_nop 1
	v_cndmask_b32_e64 v153, v153, v155, s[8:9]
	v_rsq_f32_e32 v153, v153
	s_nop 0
	v_mul_f32_e32 v155, 0x45800000, v153
	v_cndmask_b32_e64 v180, v153, v155, s[8:9]
	v_pk_mul_f32 v[160:161], v[164:165], v[180:181] op_sel_hi:[1,0]
	v_pk_mul_f32 v[164:165], v[166:167], v[180:181] op_sel_hi:[1,0]
	v_pk_mul_f32 v[176:177], v[176:177], v[160:161]
	v_pk_mul_f32 v[160:161], v[178:179], v[164:165]
	v_cvt_pk_bf16_f32 v164, v176, v177
	v_cvt_pk_bf16_f32 v165, v160, v161
	global_store_dwordx2 v[158:159], v[164:165], off
	v_accvgpr_read_b32 v164, a216
	v_accvgpr_read_b32 v165, a217
	v_accvgpr_read_b32 v166, a218
	v_accvgpr_read_b32 v167, a219
	v_pk_mul_f32 v[168:169], v[168:169], v[180:181] op_sel_hi:[1,0]
	v_pk_mul_f32 v[170:171], v[170:171], v[180:181] op_sel_hi:[1,0]
	v_pk_mul_f32 v[172:173], v[172:173], v[180:181] op_sel_hi:[1,0]
	v_pk_mul_f32 v[174:175], v[174:175], v[180:181] op_sel_hi:[1,0]
	v_pk_mul_f32 v[178:179], v[130:131], v[180:181] op_sel_hi:[1,0]
	v_pk_mul_f32 v[180:181], v[132:133], v[180:181] op_sel_hi:[1,0]
	v_fma_f32 v153, v2, v176, 0
	v_fma_f32 v155, v3, v176, 0
	v_fma_f32 v163, v4, v176, 0
	v_fma_f32 v182, v5, v176, 0
	v_fma_f32 v183, v6, v176, 0
	v_fma_f32 v184, v176, v7, 0
	v_fma_f32 v185, v176, v8, 0
	v_fma_f32 v176, v176, v9, 0
	v_fmac_f32_e32 v153, v177, v10
	v_fmac_f32_e32 v155, v177, v11
	v_fmac_f32_e32 v163, v177, v12
	v_fmac_f32_e32 v182, v177, v13
	v_fmac_f32_e32 v183, v177, v14
	v_fmac_f32_e32 v184, v177, v15
	v_fmac_f32_e32 v185, v177, v16
	v_fmac_f32_e32 v176, v177, v17
	v_fmac_f32_e32 v153, v160, v18
	v_fmac_f32_e32 v155, v160, v19
	v_fmac_f32_e32 v163, v160, v20
	v_fmac_f32_e32 v182, v160, v21
	v_fmac_f32_e32 v183, v160, v22
	v_fmac_f32_e32 v184, v160, v23
	v_fmac_f32_e32 v185, v160, v24
	v_fmac_f32_e32 v176, v160, v25
	v_fmac_f32_e32 v153, v161, v26
	v_fmac_f32_e32 v155, v161, v27
	v_fmac_f32_e32 v163, v161, v28
	v_fmac_f32_e32 v182, v161, v29
	v_fmac_f32_e32 v183, v161, v30
	v_fmac_f32_e32 v184, v161, v31
	v_fmac_f32_e32 v185, v161, v32
	v_fmac_f32_e32 v176, v161, v33
	v_pk_mul_f32 v[168:169], v[168:169], v[164:165]
	v_pk_mul_f32 v[170:171], v[170:171], v[166:167]
	v_cvt_pk_bf16_f32 v164, v168, v169
	v_cvt_pk_bf16_f32 v165, v170, v171
	global_store_dwordx2 v[158:159], v[164:165], off offset:512
	v_accvgpr_read_b32 v164, a220
	v_accvgpr_read_b32 v165, a221
	v_accvgpr_read_b32 v166, a222
; __device__ __forceinline__ float wsum(float v) { v = dpp_row_sum16(v); v += __shfl_xor(v, 16); v += __shfl_xor(v, 32); return v; }
; __device__ __forceinline__ void phase0(const Params& p, char* smem) {
;     ...
;     for (int i = 0; i < 4; i++) {
;       const int k = i * 256 + lane * 4;
;       float4 g = *(const float4*)(p.g_mix + k);
;       float hv[4] = {xv[i].x * rs * g.x, xv[i].y * rs * g.y, xv[i].z * rs * g.z, xv[i].w * rs * g.w};
;       *(uint2*)(H + (size_t)row * 1024 + k) = make_uint2(pack2(hv[0], hv[1]), pack2(hv[2], hv[3]));
; #pragma unroll
;       for (int q = 0; q < 4; q++) {
;         float4 wa = *(const float4*)&w8[(k + q) * 8], wb = *(const float4*)&w8[(k + q) * 8 + 4];
;         d8[0] += hv[q] * wa.x; d8[1] += hv[q] * wa.y; d8[2] += hv[q] * wa.z; d8[3] += hv[q] * wa.w;
;         d8[4] += hv[q] * wb.x; d8[5] += hv[q] * wb.y; d8[6] += hv[q] * wb.z; d8[7] += hv[q] * wb.w;
;       }
;     }
; #pragma unroll
;     for (int j = 0; j < 8; j++) d8[j] = wsum(d8[j]);
	v_accvgpr_read_b32 v167, a223
	v_fmac_f32_e32 v153, v168, v34
	v_fmac_f32_e32 v155, v168, v35
	v_fmac_f32_e32 v163, v168, v36
	v_fmac_f32_e32 v182, v168, v37
	v_fmac_f32_e32 v183, v168, v38
	v_fmac_f32_e32 v184, v168, v39
	v_fmac_f32_e32 v185, v168, v40
	v_fmac_f32_e32 v176, v168, v41
	v_fmac_f32_e32 v153, v169, v42
	v_fmac_f32_e32 v155, v169, v43
	v_fmac_f32_e32 v163, v169, v44
	v_fmac_f32_e32 v182, v169, v45
	v_fmac_f32_e32 v183, v169, v46
	v_fmac_f32_e32 v184, v169, v47
	v_fmac_f32_e32 v185, v169, v48
	v_fmac_f32_e32 v176, v169, v49
	v_fmac_f32_e32 v153, v170, v50
	v_fmac_f32_e32 v155, v170, v51
	v_fmac_f32_e32 v163, v170, v52
	v_fmac_f32_e32 v182, v170, v53
	v_fmac_f32_e32 v183, v170, v54
	v_fmac_f32_e32 v184, v170, v55
	v_fmac_f32_e32 v185, v170, v56
	v_fmac_f32_e32 v176, v170, v57
	v_fmac_f32_e32 v153, v171, v58
	v_fmac_f32_e32 v155, v171, v59
	v_fmac_f32_e32 v163, v171, v60
	v_fmac_f32_e32 v182, v171, v61
	v_fmac_f32_e32 v183, v171, v62
	v_fmac_f32_e32 v184, v171, v63
	v_fmac_f32_e32 v185, v171, v64
	v_fmac_f32_e32 v176, v171, v65
	v_pk_mul_f32 v[164:165], v[172:173], v[164:165]
	v_pk_mul_f32 v[166:167], v[174:175], v[166:167]
	v_cvt_pk_bf16_f32 v130, v164, v165
	v_cvt_pk_bf16_f32 v131, v166, v167
	global_store_dwordx2 v[158:159], v[130:131], off offset:1024
	v_accvgpr_read_b32 v130, a224
	v_accvgpr_read_b32 v131, a225
	v_accvgpr_read_b32 v132, a226
	v_accvgpr_read_b32 v133, a227
	v_fmac_f32_e32 v153, v164, v66
	v_fmac_f32_e32 v155, v164, v67
	v_fmac_f32_e32 v163, v164, v68
	v_fmac_f32_e32 v182, v164, v69
	v_fmac_f32_e32 v183, v164, v70
	v_fmac_f32_e32 v184, v164, v71
	v_fmac_f32_e32 v185, v164, v72
	v_fmac_f32_e32 v176, v164, v73
	v_fmac_f32_e32 v153, v165, v74
	v_fmac_f32_e32 v155, v165, v75
	v_fmac_f32_e32 v163, v165, v76
	v_fmac_f32_e32 v182, v165, v77
	v_fmac_f32_e32 v183, v165, v78
	v_fmac_f32_e32 v184, v165, v79
	v_fmac_f32_e32 v185, v165, v80
	v_fmac_f32_e32 v176, v165, v81
	v_fmac_f32_e32 v153, v166, v82
	v_fmac_f32_e32 v155, v166, v83
	v_fmac_f32_e32 v163, v166, v84
	v_fmac_f32_e32 v182, v166, v85
	v_fmac_f32_e32 v183, v166, v86
	v_fmac_f32_e32 v184, v166, v87
	v_fmac_f32_e32 v185, v166, v88
	v_fmac_f32_e32 v176, v166, v89
	v_fmac_f32_e32 v153, v167, v90
	v_fmac_f32_e32 v155, v167, v91
	v_fmac_f32_e32 v163, v167, v92
	v_fmac_f32_e32 v182, v167, v93
	v_fmac_f32_e32 v183, v167, v94
	v_fmac_f32_e32 v184, v167, v95
	v_fmac_f32_e32 v185, v167, v96
	v_fmac_f32_e32 v176, v167, v97
	v_pk_mul_f32 v[172:173], v[178:179], v[130:131]
	s_nop 0
	v_fmac_f32_e32 v153, v172, v98
	v_fmac_f32_e32 v155, v172, v99
	v_fmac_f32_e32 v163, v172, v100
	v_fmac_f32_e32 v182, v172, v101
	v_fmac_f32_e32 v183, v172, v102
	v_fmac_f32_e32 v184, v172, v103
	v_fmac_f32_e32 v185, v172, v104
	v_fmac_f32_e32 v176, v172, v105
	v_pk_mul_f32 v[174:175], v[180:181], v[132:133]
	v_fmac_f32_e32 v153, v173, v106
	v_fmac_f32_e32 v155, v173, v107
	v_fmac_f32_e32 v163, v173, v108
	v_fmac_f32_e32 v182, v173, v109
	v_fmac_f32_e32 v183, v173, v110
	v_fmac_f32_e32 v184, v173, v111
	v_fmac_f32_e32 v185, v173, v112
	v_fmac_f32_e32 v176, v173, v113
	v_fmac_f32_e32 v153, v174, v114
	v_fmac_f32_e32 v155, v174, v115
	v_fmac_f32_e32 v163, v174, v116
	v_fmac_f32_e32 v182, v174, v117
	v_fmac_f32_e32 v183, v174, v118
	v_fmac_f32_e32 v184, v174, v119
	v_fmac_f32_e32 v185, v174, v120
	v_fmac_f32_e32 v176, v174, v121
	v_fmac_f32_e32 v153, v175, v122
	v_fmac_f32_e32 v155, v175, v123
	v_fmac_f32_e32 v163, v175, v124
	v_fmac_f32_e32 v182, v175, v125
	v_fmac_f32_e32 v183, v175, v126
	v_fmac_f32_e32 v184, v175, v127
	v_fmac_f32_e32 v185, v175, v128
	v_fmac_f32_e32 v176, v175, v129
	v_add_f32_dpp v130, v153, v153 quad_perm:[1,0,3,2] row_mask:0xf bank_mask:0xf bound_ctrl:1
	v_add_f32_dpp v131, v155, v155 quad_perm:[1,0,3,2] row_mask:0xf bank_mask:0xf bound_ctrl:1
	v_add_f32_dpp v132, v163, v163 quad_perm:[1,0,3,2] row_mask:0xf bank_mask:0xf bound_ctrl:1
	v_add_f32_dpp v133, v182, v182 quad_perm:[1,0,3,2] row_mask:0xf bank_mask:0xf bound_ctrl:1
	v_add_f32_dpp v153, v183, v183 quad_perm:[1,0,3,2] row_mask:0xf bank_mask:0xf bound_ctrl:1
	v_add_f32_dpp v155, v184, v184 quad_perm:[1,0,3,2] row_mask:0xf bank_mask:0xf bound_ctrl:1
	v_add_f32_dpp v160, v185, v185 quad_perm:[1,0,3,2] row_mask:0xf bank_mask:0xf bound_ctrl:1
	v_add_f32_dpp v161, v176, v176 quad_perm:[1,0,3,2] row_mask:0xf bank_mask:0xf bound_ctrl:1
	v_add_f32_dpp v130, v130, v130 quad_perm:[2,3,0,1] row_mask:0xf bank_mask:0xf bound_ctrl:1
	v_add_f32_dpp v131, v131, v131 quad_perm:[2,3,0,1] row_mask:0xf bank_mask:0xf bound_ctrl:1
	v_add_f32_dpp v132, v132, v132 quad_perm:[2,3,0,1] row_mask:0xf bank_mask:0xf bound_ctrl:1
	v_add_f32_dpp v133, v133, v133 quad_perm:[2,3,0,1] row_mask:0xf bank_mask:0xf bound_ctrl:1
	v_add_f32_dpp v153, v153, v153 quad_perm:[2,3,0,1] row_mask:0xf bank_mask:0xf bound_ctrl:1
	v_add_f32_dpp v155, v155, v155 quad_perm:[2,3,0,1] row_mask:0xf bank_mask:0xf bound_ctrl:1
	v_add_f32_dpp v160, v160, v160 quad_perm:[2,3,0,1] row_mask:0xf bank_mask:0xf bound_ctrl:1
	v_add_f32_dpp v161, v161, v161 quad_perm:[2,3,0,1] row_mask:0xf bank_mask:0xf bound_ctrl:1
	v_add_f32_dpp v130, v130, v130 row_half_mirror row_mask:0xf bank_mask:0xf bound_ctrl:1
	v_add_f32_dpp v131, v131, v131 row_half_mirror row_mask:0xf bank_mask:0xf bound_ctrl:1
	v_add_f32_dpp v132, v132, v132 row_half_mirror row_mask:0xf bank_mask:0xf bound_ctrl:1
	v_add_f32_dpp v133, v133, v133 row_half_mirror row_mask:0xf bank_mask:0xf bound_ctrl:1
	v_add_f32_dpp v153, v153, v153 row_half_mirror row_mask:0xf bank_mask:0xf bound_ctrl:1
	v_add_f32_dpp v155, v155, v155 row_half_mirror row_mask:0xf bank_mask:0xf bound_ctrl:1
	v_add_f32_dpp v160, v160, v160 row_half_mirror row_mask:0xf bank_mask:0xf bound_ctrl:1
	v_add_f32_dpp v161, v161, v161 row_half_mirror row_mask:0xf bank_mask:0xf bound_ctrl:1
	v_add_f32_dpp v130, v130, v130 row_mirror row_mask:0xf bank_mask:0xf bound_ctrl:1
	v_add_f32_dpp v131, v131, v131 row_mirror row_mask:0xf bank_mask:0xf bound_ctrl:1
	v_add_f32_dpp v132, v132, v132 row_mirror row_mask:0xf bank_mask:0xf bound_ctrl:1
	v_add_f32_dpp v133, v133, v133 row_mirror row_mask:0xf bank_mask:0xf bound_ctrl:1
	v_add_f32_dpp v163, v153, v153 row_mirror row_mask:0xf bank_mask:0xf bound_ctrl:1
	v_add_f32_dpp v155, v155, v155 row_mirror row_mask:0xf bank_mask:0xf bound_ctrl:1
	v_add_f32_dpp v160, v160, v160 row_mirror row_mask:0xf bank_mask:0xf bound_ctrl:1
	v_add_f32_dpp v161, v161, v161 row_mirror row_mask:0xf bank_mask:0xf bound_ctrl:1
	ds_bpermute_b32 v153, v1, v130
	ds_bpermute_b32 v164, v1, v131
	ds_bpermute_b32 v165, v1, v132
	ds_bpermute_b32 v166, v1, v133
	ds_bpermute_b32 v167, v1, v163
	ds_bpermute_b32 v168, v1, v155
	ds_bpermute_b32 v169, v1, v160
	ds_bpermute_b32 v170, v1, v161
	s_waitcnt lgkmcnt(7)
; __device__ __forceinline__ float wsum(float v) { v = dpp_row_sum16(v); v += __shfl_xor(v, 16); v += __shfl_xor(v, 32); return v; }
; __device__ __forceinline__ float sigmoidf_(float x) { return __builtin_amdgcn_rcpf(1.f + __expf(-x)); }
; __device__ __forceinline__ void phase0(const Params& p, char* smem) {
;     ...
;     for (int j = 0; j < 8; j++) d8[j] = wsum(d8[j]);
;     if (lane < 4) {
;       float bb = lane == 0 ? d8[0] : lane == 1 ? d8[1] : lane == 2 ? d8[2] : d8[3];
;       float ab = lane == 0 ? d8[4] : lane == 1 ? d8[5] : lane == 2 ? d8[6] : d8[7];
;       BETA[row * 4 + lane] = sigmoidf_(bb);
;       float z = ab + p.dt_bias[lane];
;       float sp = z > 20.f ? z : log1pf(expf(z));
	v_add_f32_e32 v153, v130, v153
	s_waitcnt lgkmcnt(6)
	v_add_f32_e32 v164, v131, v164
	s_waitcnt lgkmcnt(5)
	v_add_f32_e32 v165, v132, v165
	s_waitcnt lgkmcnt(4)
	v_add_f32_e32 v166, v133, v166
	s_waitcnt lgkmcnt(3)
	v_add_f32_e32 v130, v163, v167
	s_waitcnt lgkmcnt(2)
	v_add_f32_e32 v131, v155, v168
	s_waitcnt lgkmcnt(1)
	v_add_f32_e32 v132, v160, v169
	s_waitcnt lgkmcnt(0)
	v_add_f32_e32 v133, v161, v170
	ds_bpermute_b32 v167, v134, v153
	ds_bpermute_b32 v168, v134, v164
	ds_bpermute_b32 v169, v134, v165
	ds_bpermute_b32 v170, v134, v166
	ds_bpermute_b32 v155, v134, v130
	ds_bpermute_b32 v160, v134, v131
	ds_bpermute_b32 v161, v134, v132
	ds_bpermute_b32 v163, v134, v133
	v_cvt_pk_bf16_f32 v172, v172, v173
	v_cvt_pk_bf16_f32 v173, v174, v175
	global_store_dwordx2 v[158:159], v[172:173], off offset:1536
	s_and_saveexec_b64 s[12:13], vcc
	s_cbranch_execz .LBB0_104
	s_waitcnt lgkmcnt(4)
	v_add_f32_e32 v158, v166, v170
	v_add_f32_e32 v159, v165, v169
	v_add_f32_e32 v164, v164, v168
	v_cndmask_b32_e64 v158, v158, v159, s[6:7]
	v_add_f32_e32 v153, v153, v167
	v_cndmask_b32_e64 v158, v158, v164, s[4:5]
	v_cndmask_b32_e64 v153, v158, v153, s[0:1]
	v_mul_f32_e32 v153, 0xbfb8aa3b, v153
	v_exp_f32_e32 v153, v153
	v_readlane_b32 s8, v254, 36
	v_readlane_b32 s9, v254, 37
	s_waitcnt lgkmcnt(0)
	v_add_f32_e32 v133, v133, v163
	v_add_f32_e32 v153, 1.0, v153
	v_rcp_f32_e32 v164, v153
	v_ashrrev_i32_e32 v153, 31, v152
	v_lshl_add_u64 v[158:159], v[152:153], 2, s[8:9]
	v_add_f32_e32 v132, v132, v161
	global_store_dword v[158:159], v164, off
	v_accvgpr_read_b32 v158, a228
	v_add_f32_e32 v131, v131, v160
	v_cndmask_b32_e64 v132, v133, v132, s[6:7]
	v_add_f32_e32 v130, v130, v155
	v_cndmask_b32_e64 v131, v132, v131, s[4:5]
	v_cndmask_b32_e64 v130, v131, v130, s[0:1]
	v_add_f32_e32 v130, v130, v158
	v_cmp_nlt_f32_e64 s[8:9], s20, v130
	s_and_saveexec_b64 s[14:15], s[8:9]
	s_cbranch_execz .LBB0_103
	v_mul_f32_e32 v131, 0x3fb8aa3b, v130
	v_rndne_f32_e32 v132, v131
	v_sub_f32_e32 v133, v131, v132
	v_fma_f32 v131, v130, s21, -v131
	v_fmac_f32_e32 v131, 0x32a5705f, v130
	v_add_f32_e32 v131, v133, v131
	v_cvt_i32_f32_e32 v132, v132
	v_exp_f32_e32 v131, v131
	v_cmp_ngt_f32_e64 s[8:9], s22, v130
	v_ldexp_f32 v131, v131, v132
	s_nop 0
	v_cndmask_b32_e64 v131, 0, v131, s[8:9]
	v_cmp_nlt_f32_e64 s[8:9], s23, v130
	s_nop 1
	v_cndmask_b32_e64 v163, v162, v131, s[8:9]
	v_add_f32_e32 v132, 1.0, v163
	v_add_f32_e32 v130, -1.0, v132
	v_sub_f32_e32 v131, v130, v132
	v_add_f32_e32 v131, 1.0, v131
	v_sub_f32_e32 v130, v163, v130
	v_add_f32_e32 v133, v130, v131
	v_frexp_mant_f32_e32 v155, v132
	v_cvt_f64_f32_e32 v[130:131], v132
	v_frexp_exp_i32_f64_e32 v130, v[130:131]
	v_cmp_gt_f32_e64 s[8:9], s25, v155
	s_nop 1
	v_subbrev_co_u32_e64 v164, s[8:9], 0, v130, s[8:9]
	v_sub_u32_e32 v130, 0, v164
	v_ldexp_f32 v131, v132, v130
	v_add_f32_e32 v132, -1.0, v131
	v_add_f32_e32 v155, 1.0, v131
	v_ldexp_f32 v130, v133, v130
	v_add_f32_e32 v133, 1.0, v132
	v_add_f32_e32 v158, -1.0, v155
	v_sub_f32_e32 v133, v131, v133
	v_sub_f32_e32 v131, v131, v158
	v_add_f32_e32 v133, v130, v133
	v_add_f32_e32 v130, v130, v131
	v_add_f32_e32 v165, v155, v130
	v_rcp_f32_e32 v166, v165
	v_sub_f32_e32 v131, v155, v165
	v_add_f32_e32 v155, v130, v131
	v_add_f32_e32 v131, v132, v133
	v_mul_f32_e32 v168, v131, v166
	v_sub_f32_e32 v130, v132, v131
	v_mul_f32_e32 v132, v165, v168
	v_fma_f32 v158, v168, v165, -v132
	v_fmac_f32_e32 v158, v168, v155
	v_add_f32_e32 v167, v133, v130
	v_add_f32_e32 v130, v132, v158
	v_sub_f32_e32 v133, v131, v130
	v_pk_add_f32 v[160:161], v[130:131], v[132:133] neg_lo:[0,1] neg_hi:[0,1]
	v_mov_b32_e32 v159, v130
	v_pk_add_f32 v[130:131], v[160:161], v[158:159] neg_lo:[0,1] neg_hi:[0,1]
	v_cmp_neq_f32_e64 s[8:9], s24, v163
	v_add_f32_e32 v131, v167, v131
	v_add_f32_e32 v130, v130, v131
	v_add_f32_e32 v131, v133, v130
	v_mul_f32_e32 v167, v166, v131
	v_mul_f32_e32 v132, v165, v167
	v_fma_f32 v158, v167, v165, -v132
	v_fmac_f32_e32 v158, v167, v155
	v_sub_f32_e32 v133, v133, v131
	v_add_f32_e32 v155, v130, v133
	v_add_f32_e32 v130, v132, v158
	v_sub_f32_e32 v133, v131, v130
	v_pk_add_f32 v[160:161], v[130:131], v[132:133] neg_lo:[0,1] neg_hi:[0,1]
	v_mov_b32_e32 v159, v130
	v_pk_add_f32 v[130:131], v[160:161], v[158:159] neg_lo:[0,1] neg_hi:[0,1]
	s_nop 0
	v_add_f32_e32 v131, v155, v131
	v_add_f32_e32 v130, v130, v131
	v_add_f32_e32 v131, v168, v167
	v_add_f32_e32 v130, v133, v130
	v_sub_f32_e32 v132, v131, v168
	v_mul_f32_e32 v130, v166, v130
	v_sub_f32_e32 v132, v167, v132
	v_add_f32_e32 v132, v132, v130
	v_add_f32_e32 v158, v131, v132
	v_mul_f32_e32 v159, v158, v158
	v_fmamk_f32 v130, v159, 0x3e9b6dac, v141
	v_fmaak_f32 v155, v159, v130, 0x3f2aaada
	v_cvt_f32_i32_e32 v130, v164
	v_sub_f32_e32 v131, v158, v131
	v_sub_f32_e32 v131, v132, v131
	v_ldexp_f32 v160, v131, 1
	v_mul_f32_e32 v131, v158, v159
	v_ldexp_f32 v133, v158, 1
	v_pk_mul_f32 v[158:159], v[130:131], v[154:155]
	s_nop 0
	v_fma_f32 v132, v130, s26, -v158
	v_fmac_f32_e32 v132, 0xb102e308, v130
	v_pk_add_f32 v[130:131], v[158:159], v[132:133]
	s_nop 0
	v_sub_f32_e32 v133, v131, v133
	v_sub_f32_e32 v133, v159, v133
	v_add_f32_e32 v161, v160, v133
	v_mov_b32_e32 v160, v158
	v_pk_add_f32 v[158:159], v[130:131], v[158:159] neg_lo:[0,1] neg_hi:[0,1]
	v_pk_add_f32 v[164:165], v[130:131], v[160:161]
	v_mov_b32_e32 v133, v130
	v_mov_b32_e32 v159, v165
	v_pk_add_f32 v[166:167], v[132:133], v[158:159] neg_lo:[0,1] neg_hi:[0,1]
	v_pk_add_f32 v[132:133], v[132:133], v[158:159]
	v_mov_b32_e32 v160, v161
	v_pk_add_f32 v[158:159], v[132:133], v[130:131] op_sel:[1,0] op_sel_hi:[0,1] neg_lo:[0,1] neg_hi:[0,1]
	v_pk_add_f32 v[168:169], v[164:165], v[158:159] op_sel_hi:[1,0] neg_lo:[0,1] neg_hi:[0,1]
	v_mov_b32_e32 v164, v165
	v_mov_b32_e32 v165, v133
	v_pk_mov_b32 v[158:159], v[130:131], v[158:159] op_sel:[1,0]
	v_mov_b32_e32 v161, v130
	v_pk_add_f32 v[158:159], v[164:165], v[158:159] neg_lo:[0,1] neg_hi:[0,1]
	v_mov_b32_e32 v168, v166
	v_pk_add_f32 v[130:131], v[160:161], v[158:159] neg_lo:[0,1] neg_hi:[0,1]
	v_mov_b32_e32 v167, v133
	v_pk_add_f32 v[158:159], v[168:169], v[130:131]
	s_nop 0
	v_pk_add_f32 v[160:161], v[158:159], v[158:159] op_sel:[0,1] op_sel_hi:[1,0]
	s_nop 0
	v_pk_add_f32 v[132:133], v[132:133], v[160:161] op_sel:[1,0] op_sel_hi:[0,1]
	v_mov_b32_e32 v159, v132
	v_pk_add_f32 v[164:165], v[158:159], v[166:167] neg_lo:[0,1] neg_hi:[0,1]
	v_mov_b32_e32 v131, v160
	v_sub_f32_e32 v133, v158, v164
	v_pk_add_f32 v[130:131], v[130:131], v[164:165] neg_lo:[0,1] neg_hi:[0,1]
	v_sub_f32_e32 v133, v166, v133
	v_add_f32_e32 v130, v130, v133
	v_add_f32_e32 v130, v130, v131
	v_add_f32_e32 v130, v132, v130
	v_cndmask_b32_e64 v130, v162, v130, s[8:9]
	v_cmp_lt_f32_e64 s[8:9], |v163|, s27
	s_nop 1
	v_cndmask_b32_e64 v130, v130, v163, s[8:9]
; __device__ __forceinline__ void phase0(const Params& p, char* smem) {
;     ...
;       float z = ab + p.dt_bias[lane];
;       float sp = z > 20.f ? z : log1pf(expf(z));
;       GLOG[row * 4 + lane] = -expf(p.a_log[lane]) * sp;
.LBB0_103:
	s_or_b64 exec, exec, s[14:15]
	v_accvgpr_read_b32 v131, a229
	v_mul_f32_e32 v132, 0x3fb8aa3b, v131
	v_rndne_f32_e32 v133, v132
	v_fma_f32 v155, v131, s21, -v132
	v_sub_f32_e32 v132, v132, v133
	v_fmac_f32_e32 v155, 0x32a5705f, v131
	v_add_f32_e32 v132, v132, v155
	v_cvt_i32_f32_e32 v133, v133
	v_exp_f32_e32 v132, v132
	v_cmp_ngt_f32_e64 s[8:9], s22, v131
	v_ldexp_f32 v132, v132, v133
	s_nop 0
	v_cndmask_b32_e64 v132, 0, v132, s[8:9]
	v_cmp_nlt_f32_e64 s[8:9], s23, v131
	s_nop 1
	v_cndmask_b32_e64 v131, v162, v132, s[8:9]
	v_readlane_b32 s8, v254, 38
	v_readlane_b32 s9, v254, 39
	v_mul_f32_e64 v132, v130, -v131
	s_nop 0
	v_lshl_add_u64 v[130:131], v[152:153], 2, s[8:9]
	global_store_dword v[130:131], v132, off

; __device__ __forceinline__ u16 f2bf(float f) { return (u16)(pack2(f, f) & 0xffffu); }
; __device__ __forceinline__ float siluf_(float x) { return x * __builtin_amdgcn_rcpf(1.f + __expf(-x)); }
; __device__ __forceinline__ int rowmap(int e, int lane) { return (e & 3) + 8 * (e >> 2) + 4 * (lane >> 5); }
; __device__ __forceinline__ void phase1(const Params& p, char* smem) {
;     ...
;     } else {
;       u16* T = (u16*)smem;
;       const bool act = (seg == 0 || seg == 3 || seg == 7);
; #pragma unroll
;       for (int i = 0; i < 2; i++)
; #pragma unroll
;         for (int j = 0; j < 2; j++) {
;           const int cl = wn * 64 + j * 32 + (lane & 31);
; #pragma unroll
;           for (int e = 0; e < 16; e++) {
;             const float v = acc[i][j][e];
;             const int rl = wm * 64 + i * 32 + rowmap(e, lane);
;             T[rl * 136 + cl] = f2bf(act ? siluf_(v) : v);
;             if (seg >= 4 && seg <= 6) {
;               const int row = m0 + rl; const int ch = (seg - 4) * 512 + cb + cl;
;               if (row < NTP) { int t = row & 2047; if (t >= 2045) p.out[OUT_CP + ((size_t)(row >> 11) * 3 + (t - 2045)) * 1536 + ch] = v; }
;               else { int rs = row - NTP; int t = rs & 3; if (t >= 1) p.out[OUT_CS + ((size_t)(rs >> 2) * 3 + (t - 1)) * 1536 + ch] = v; }
;             }
;           }
.LBB0_177:
	s_lshl_b32 s0, s35, 7
	s_lshr_b32 s17, s6, 2
	s_and_b32 s2, s0, 0x180
	v_accvgpr_read_b32 v100, a0
	v_accvgpr_read_b32 v99, a1
	v_accvgpr_read_b32 v98, a2
	v_accvgpr_read_b32 v97, a3
	v_accvgpr_read_b32 v96, a4
	v_accvgpr_read_b32 v95, a5
	v_accvgpr_read_b32 v94, a6
	v_accvgpr_read_b32 v93, a7
	v_accvgpr_read_b32 v92, a8
	v_accvgpr_read_b32 v91, a9
	v_accvgpr_read_b32 v90, a10
	v_accvgpr_read_b32 v89, a11
	v_accvgpr_read_b32 v88, a12
	v_accvgpr_read_b32 v87, a13
	v_accvgpr_read_b32 v86, a14
	v_accvgpr_read_b32 v19, a15
	v_accvgpr_read_b32 v116, a16
	v_accvgpr_read_b32 v115, a17
	v_accvgpr_read_b32 v114, a18
	v_accvgpr_read_b32 v113, a19
	v_accvgpr_read_b32 v112, a20
	v_accvgpr_read_b32 v111, a21
	v_accvgpr_read_b32 v110, a22
	v_accvgpr_read_b32 v109, a23
	v_accvgpr_read_b32 v108, a24
	v_accvgpr_read_b32 v107, a25
	v_accvgpr_read_b32 v106, a26
	v_accvgpr_read_b32 v105, a27
	v_accvgpr_read_b32 v104, a28
	v_accvgpr_read_b32 v103, a29
	v_accvgpr_read_b32 v102, a30
	v_accvgpr_read_b32 v101, a31
	v_accvgpr_read_b32 v190, a32
	v_accvgpr_read_b32 v189, a33
	v_accvgpr_read_b32 v188, a34
	v_accvgpr_read_b32 v187, a35
	v_accvgpr_read_b32 v186, a36
	v_accvgpr_read_b32 v185, a37
	v_accvgpr_read_b32 v184, a38
	v_accvgpr_read_b32 v183, a39
	v_accvgpr_read_b32 v182, a40
	v_accvgpr_read_b32 v181, a41
	v_accvgpr_read_b32 v180, a42
	v_accvgpr_read_b32 v179, a43
	v_accvgpr_read_b32 v178, a44
	v_accvgpr_read_b32 v177, a45
	v_accvgpr_read_b32 v176, a46
	v_accvgpr_read_b32 v117, a47
	v_accvgpr_read_b32 v215, a48
	v_accvgpr_read_b32 v210, a49
	v_accvgpr_read_b32 v208, a50
	v_accvgpr_read_b32 v206, a51
	v_accvgpr_read_b32 v204, a52
	v_accvgpr_read_b32 v203, a53
	v_accvgpr_read_b32 v202, a54
	v_accvgpr_read_b32 v200, a55
	v_accvgpr_read_b32 v198, a56
	v_accvgpr_read_b32 v197, a57
	v_accvgpr_read_b32 v196, a58
	v_accvgpr_read_b32 v195, a59
	v_accvgpr_read_b32 v194, a60
	v_accvgpr_read_b32 v193, a61
	v_accvgpr_read_b32 v192, a62
	v_accvgpr_read_b32 v191, a63
	s_cmp_lg_u32 s17, 1
	s_mov_b64 s[0:1], -1
	s_cbranch_scc0 .LBB0_711
	s_cmp_lt_u32 s17, 4
	s_cbranch_scc1 .Lp1_fast
	s_cmp_gt_u32 s17, 6
	s_cbranch_scc1 .Lp1_fast
	s_cmp_ge_u32 s16, 0x4000
	s_cbranch_scc1 .Lp1_generic
	s_and_b32 s0, s16, 0x780
	s_cmp_eq_u32 s0, 0x780
	s_cbranch_scc1 .Lp1_generic
.Lp1_fast:
	s_cmp_eq_u32 s17, 0
	s_cbranch_scc1 .Lp1_fast_act
	s_cmp_eq_u32 s17, 3
	s_cbranch_scc1 .Lp1_fast_act
	s_cmp_eq_u32 s17, 7
	s_cbranch_scc1 .Lp1_fast_act
	v_accvgpr_read_b32 v86, a48
	v_accvgpr_read_b32 v87, a49
	v_accvgpr_read_b32 v88, a50
	v_accvgpr_read_b32 v89, a51
	v_accvgpr_read_b32 v90, a52
	v_accvgpr_read_b32 v91, a53
	v_accvgpr_read_b32 v92, a54
	v_accvgpr_read_b32 v93, a55
	v_cvt_pk_bf16_f32 v86, v86, v86
	v_cvt_pk_bf16_f32 v87, v87, v87
	v_cvt_pk_bf16_f32 v88, v88, v88
	v_cvt_pk_bf16_f32 v89, v89, v89
	v_cvt_pk_bf16_f32 v90, v90, v90
	v_cvt_pk_bf16_f32 v91, v91, v91
	v_cvt_pk_bf16_f32 v92, v92, v92
	v_cvt_pk_bf16_f32 v93, v93, v93
	ds_write_b16 v249, v86
	ds_write_b16 v249, v87 offset:272
	ds_write_b16 v249, v88 offset:544
	ds_write_b16 v249, v89 offset:816
	ds_write_b16 v250, v90
	ds_write_b16 v250, v91 offset:272
	ds_write_b16 v250, v92 offset:544
	ds_write_b16 v250, v93 offset:816
	v_accvgpr_read_b32 v86, a56
	v_accvgpr_read_b32 v87, a57
	v_accvgpr_read_b32 v88, a58
	v_accvgpr_read_b32 v89, a59
	v_accvgpr_read_b32 v90, a60
	v_accvgpr_read_b32 v91, a61
	v_accvgpr_read_b32 v92, a62
	v_accvgpr_read_b32 v93, a63
	v_cvt_pk_bf16_f32 v86, v86, v86
	v_cvt_pk_bf16_f32 v87, v87, v87
	v_cvt_pk_bf16_f32 v88, v88, v88
	v_cvt_pk_bf16_f32 v89, v89, v89
	v_cvt_pk_bf16_f32 v90, v90, v90
	v_cvt_pk_bf16_f32 v91, v91, v91
	v_cvt_pk_bf16_f32 v92, v92, v92
	v_cvt_pk_bf16_f32 v93, v93, v93
	ds_write_b16 v251, v86
	ds_write_b16 v251, v87 offset:272
	ds_write_b16 v251, v88 offset:544
	ds_write_b16 v251, v89 offset:816
	ds_write_b16 v252, v90
	ds_write_b16 v252, v91 offset:272
	ds_write_b16 v252, v92 offset:544
	ds_write_b16 v252, v93 offset:816
	v_accvgpr_read_b32 v86, a32
	v_accvgpr_read_b32 v87, a33
	v_accvgpr_read_b32 v88, a34
	v_accvgpr_read_b32 v89, a35
	v_accvgpr_read_b32 v90, a36
	v_accvgpr_read_b32 v91, a37
	v_accvgpr_read_b32 v92, a38
	v_accvgpr_read_b32 v93, a39
	v_cvt_pk_bf16_f32 v86, v86, v86
	v_cvt_pk_bf16_f32 v87, v87, v87
	v_cvt_pk_bf16_f32 v88, v88, v88
	v_cvt_pk_bf16_f32 v89, v89, v89
	v_cvt_pk_bf16_f32 v90, v90, v90
	v_cvt_pk_bf16_f32 v91, v91, v91
	v_cvt_pk_bf16_f32 v92, v92, v92
	v_cvt_pk_bf16_f32 v93, v93, v93
	ds_write_b16 v249, v86 offset:64
	ds_write_b16 v249, v87 offset:336
	ds_write_b16 v249, v88 offset:608
	ds_write_b16 v249, v89 offset:880
	ds_write_b16 v250, v90 offset:64
	ds_write_b16 v250, v91 offset:336
	ds_write_b16 v250, v92 offset:608
	ds_write_b16 v250, v93 offset:880
	v_accvgpr_read_b32 v86, a40
	v_accvgpr_read_b32 v87, a41
	v_accvgpr_read_b32 v88, a42
	v_accvgpr_read_b32 v89, a43
	v_accvgpr_read_b32 v90, a44
	v_accvgpr_read_b32 v91, a45
	v_accvgpr_read_b32 v92, a46
	v_accvgpr_read_b32 v93, a47
	v_cvt_pk_bf16_f32 v86, v86, v86
	v_cvt_pk_bf16_f32 v87, v87, v87
	v_cvt_pk_bf16_f32 v88, v88, v88
	v_cvt_pk_bf16_f32 v89, v89, v89
	v_cvt_pk_bf16_f32 v90, v90, v90
	v_cvt_pk_bf16_f32 v91, v91, v91
	v_cvt_pk_bf16_f32 v92, v92, v92
	v_cvt_pk_bf16_f32 v93, v93, v93
	ds_write_b16 v251, v86 offset:64
	ds_write_b16 v251, v87 offset:336
	ds_write_b16 v251, v88 offset:608
	ds_write_b16 v251, v89 offset:880
	ds_write_b16 v252, v90 offset:64
	ds_write_b16 v252, v91 offset:336
	ds_write_b16 v252, v92 offset:608
	ds_write_b16 v252, v93 offset:880
	v_accvgpr_read_b32 v86, a16
	v_accvgpr_read_b32 v87, a17
	v_accvgpr_read_b32 v88, a18
	v_accvgpr_read_b32 v89, a19
	v_accvgpr_read_b32 v90, a20
; __device__ __forceinline__ u16 f2bf(float f) { return (u16)(pack2(f, f) & 0xffffu); }
; __device__ __forceinline__ float siluf_(float x) { return x * __builtin_amdgcn_rcpf(1.f + __expf(-x)); }
; __device__ __forceinline__ int rowmap(int e, int lane) { return (e & 3) + 8 * (e >> 2) + 4 * (lane >> 5); }
; __device__ __forceinline__ void phase1(const Params& p, char* smem) {
;     ...
;       u16* T = (u16*)smem;
;       const bool act = (seg == 0 || seg == 3 || seg == 7);
; #pragma unroll
;       for (int i = 0; i < 2; i++)
; #pragma unroll
;         for (int j = 0; j < 2; j++) {
;           const int cl = wn * 64 + j * 32 + (lane & 31);
; #pragma unroll
;           for (int e = 0; e < 16; e++) {
;             const float v = acc[i][j][e];
;             const int rl = wm * 64 + i * 32 + rowmap(e, lane);
;             T[rl * 136 + cl] = f2bf(act ? siluf_(v) : v);
	v_accvgpr_read_b32 v91, a21
	v_accvgpr_read_b32 v92, a22
	v_accvgpr_read_b32 v93, a23
	v_cvt_pk_bf16_f32 v86, v86, v86
	v_cvt_pk_bf16_f32 v87, v87, v87
	v_cvt_pk_bf16_f32 v88, v88, v88
	v_cvt_pk_bf16_f32 v89, v89, v89
	v_cvt_pk_bf16_f32 v90, v90, v90
	v_cvt_pk_bf16_f32 v91, v91, v91
	v_cvt_pk_bf16_f32 v92, v92, v92
	v_cvt_pk_bf16_f32 v93, v93, v93
	ds_write_b16 v253, v86
	ds_write_b16 v253, v87 offset:272
	ds_write_b16 v253, v88 offset:544
	ds_write_b16 v253, v89 offset:816
	ds_write_b16 v214, v90
	ds_write_b16 v214, v91 offset:272
	ds_write_b16 v214, v92 offset:544
	ds_write_b16 v214, v93 offset:816
	v_accvgpr_read_b32 v86, a24
	v_accvgpr_read_b32 v87, a25
	v_accvgpr_read_b32 v88, a26
	v_accvgpr_read_b32 v89, a27
	v_accvgpr_read_b32 v90, a28
	v_accvgpr_read_b32 v91, a29
	v_accvgpr_read_b32 v92, a30
	v_accvgpr_read_b32 v93, a31
	v_cvt_pk_bf16_f32 v86, v86, v86
	v_cvt_pk_bf16_f32 v87, v87, v87
	v_cvt_pk_bf16_f32 v88, v88, v88
	v_cvt_pk_bf16_f32 v89, v89, v89
	v_cvt_pk_bf16_f32 v90, v90, v90
	v_cvt_pk_bf16_f32 v91, v91, v91
	v_cvt_pk_bf16_f32 v92, v92, v92
	v_cvt_pk_bf16_f32 v93, v93, v93
	ds_write_b16 v216, v86
	ds_write_b16 v216, v87 offset:272
	ds_write_b16 v216, v88 offset:544
	ds_write_b16 v216, v89 offset:816
	ds_write_b16 v218, v90
	ds_write_b16 v218, v91 offset:272
	ds_write_b16 v218, v92 offset:544
	ds_write_b16 v218, v93 offset:816
	v_accvgpr_read_b32 v86, a0
	v_accvgpr_read_b32 v87, a1
	v_accvgpr_read_b32 v88, a2
	v_accvgpr_read_b32 v89, a3
	v_accvgpr_read_b32 v90, a4
	v_accvgpr_read_b32 v91, a5
	v_accvgpr_read_b32 v92, a6
	v_accvgpr_read_b32 v93, a7
	v_cvt_pk_bf16_f32 v86, v86, v86
	v_cvt_pk_bf16_f32 v87, v87, v87
	v_cvt_pk_bf16_f32 v88, v88, v88
	v_cvt_pk_bf16_f32 v89, v89, v89
	v_cvt_pk_bf16_f32 v90, v90, v90
	v_cvt_pk_bf16_f32 v91, v91, v91
	v_cvt_pk_bf16_f32 v92, v92, v92
	v_cvt_pk_bf16_f32 v93, v93, v93
	ds_write_b16 v253, v86 offset:64
	ds_write_b16 v253, v87 offset:336
	ds_write_b16 v253, v88 offset:608
	ds_write_b16 v253, v89 offset:880
	ds_write_b16 v214, v90 offset:64
	ds_write_b16 v214, v91 offset:336
	ds_write_b16 v214, v92 offset:608
	ds_write_b16 v214, v93 offset:880
	v_accvgpr_read_b32 v86, a8
	v_accvgpr_read_b32 v87, a9
	v_accvgpr_read_b32 v88, a10
	v_accvgpr_read_b32 v89, a11
	v_accvgpr_read_b32 v90, a12
	v_accvgpr_read_b32 v91, a13
	v_accvgpr_read_b32 v92, a14
	v_accvgpr_read_b32 v93, a15
	v_cvt_pk_bf16_f32 v86, v86, v86
	v_cvt_pk_bf16_f32 v87, v87, v87
	v_cvt_pk_bf16_f32 v88, v88, v88
	v_cvt_pk_bf16_f32 v89, v89, v89
	v_cvt_pk_bf16_f32 v90, v90, v90
	v_cvt_pk_bf16_f32 v91, v91, v91
	v_cvt_pk_bf16_f32 v92, v92, v92
	v_cvt_pk_bf16_f32 v93, v93, v93
	ds_write_b16 v216, v86 offset:64
	ds_write_b16 v216, v87 offset:336
	ds_write_b16 v216, v88 offset:608
	ds_write_b16 v216, v89 offset:880
	ds_write_b16 v218, v90 offset:64
	ds_write_b16 v218, v91 offset:336
	ds_write_b16 v218, v92 offset:608
	ds_write_b16 v218, v93 offset:880
	s_branch .Lp1_fast_done
.Lp1_fast_act:
	v_accvgpr_read_b32 v86, a48
	v_accvgpr_read_b32 v87, a49
	v_accvgpr_read_b32 v88, a50
	v_accvgpr_read_b32 v89, a51
	v_accvgpr_read_b32 v90, a52
	v_accvgpr_read_b32 v91, a53
	v_accvgpr_read_b32 v92, a54
	v_accvgpr_read_b32 v93, a55
	v_mul_f32_e32 v94, 0xbfb8aa3b, v86
	v_mul_f32_e32 v95, 0xbfb8aa3b, v87
	v_mul_f32_e32 v96, 0xbfb8aa3b, v88
	v_mul_f32_e32 v97, 0xbfb8aa3b, v89
	v_mul_f32_e32 v98, 0xbfb8aa3b, v90
	v_mul_f32_e32 v99, 0xbfb8aa3b, v91
	v_mul_f32_e32 v100, 0xbfb8aa3b, v92
	v_mul_f32_e32 v101, 0xbfb8aa3b, v93
	v_exp_f32_e32 v94, v94
	v_exp_f32_e32 v95, v95
	v_exp_f32_e32 v96, v96
	v_exp_f32_e32 v97, v97
	v_exp_f32_e32 v98, v98
	v_exp_f32_e32 v99, v99
	v_exp_f32_e32 v100, v100
	v_exp_f32_e32 v101, v101
	v_add_f32_e32 v94, 1.0, v94
	v_add_f32_e32 v95, 1.0, v95
	v_add_f32_e32 v96, 1.0, v96
	v_add_f32_e32 v97, 1.0, v97
	v_add_f32_e32 v98, 1.0, v98
	v_add_f32_e32 v99, 1.0, v99
	v_add_f32_e32 v100, 1.0, v100
	v_add_f32_e32 v101, 1.0, v101
	v_rcp_f32_e32 v94, v94
	v_rcp_f32_e32 v95, v95
	v_rcp_f32_e32 v96, v96
	v_rcp_f32_e32 v97, v97
	v_rcp_f32_e32 v98, v98
	v_rcp_f32_e32 v99, v99
	v_rcp_f32_e32 v100, v100
	v_rcp_f32_e32 v101, v101
	v_mul_f32_e32 v86, v86, v94
	v_mul_f32_e32 v87, v87, v95
	v_mul_f32_e32 v88, v88, v96
	v_mul_f32_e32 v89, v89, v97
	v_mul_f32_e32 v90, v90, v98
	v_mul_f32_e32 v91, v91, v99
	v_mul_f32_e32 v92, v92, v100
	v_mul_f32_e32 v93, v93, v101
	v_cvt_pk_bf16_f32 v86, v86, v86
	v_cvt_pk_bf16_f32 v87, v87, v87
	v_cvt_pk_bf16_f32 v88, v88, v88
	v_cvt_pk_bf16_f32 v89, v89, v89
	v_cvt_pk_bf16_f32 v90, v90, v90
	v_cvt_pk_bf16_f32 v91, v91, v91
	v_cvt_pk_bf16_f32 v92, v92, v92
	v_cvt_pk_bf16_f32 v93, v93, v93
	ds_write_b16 v249, v86
	ds_write_b16 v249, v87 offset:272
	ds_write_b16 v249, v88 offset:544
	ds_write_b16 v249, v89 offset:816
	ds_write_b16 v250, v90
	ds_write_b16 v250, v91 offset:272
	ds_write_b16 v250, v92 offset:544
	ds_write_b16 v250, v93 offset:816
	v_accvgpr_read_b32 v86, a56
	v_accvgpr_read_b32 v87, a57
	v_accvgpr_read_b32 v88, a58
	v_accvgpr_read_b32 v89, a59
	v_accvgpr_read_b32 v90, a60
	v_accvgpr_read_b32 v91, a61
	v_accvgpr_read_b32 v92, a62
	v_accvgpr_read_b32 v93, a63
	v_mul_f32_e32 v94, 0xbfb8aa3b, v86
	v_mul_f32_e32 v95, 0xbfb8aa3b, v87
	v_mul_f32_e32 v96, 0xbfb8aa3b, v88
	v_mul_f32_e32 v97, 0xbfb8aa3b, v89
	v_mul_f32_e32 v98, 0xbfb8aa3b, v90
	v_mul_f32_e32 v99, 0xbfb8aa3b, v91
	v_mul_f32_e32 v100, 0xbfb8aa3b, v92
	v_mul_f32_e32 v101, 0xbfb8aa3b, v93
	v_exp_f32_e32 v94, v94
	v_exp_f32_e32 v95, v95
	v_exp_f32_e32 v96, v96
	v_exp_f32_e32 v97, v97
	v_exp_f32_e32 v98, v98
	v_exp_f32_e32 v99, v99
	v_exp_f32_e32 v100, v100
	v_exp_f32_e32 v101, v101
	v_add_f32_e32 v94, 1.0, v94
	v_add_f32_e32 v95, 1.0, v95
	v_add_f32_e32 v96, 1.0, v96
; __device__ __forceinline__ u16 f2bf(float f) { return (u16)(pack2(f, f) & 0xffffu); }
; __device__ __forceinline__ float siluf_(float x) { return x * __builtin_amdgcn_rcpf(1.f + __expf(-x)); }
; __device__ __forceinline__ int rowmap(int e, int lane) { return (e & 3) + 8 * (e >> 2) + 4 * (lane >> 5); }
; __device__ __forceinline__ void phase1(const Params& p, char* smem) {
;     ...
;       u16* T = (u16*)smem;
;       const bool act = (seg == 0 || seg == 3 || seg == 7);
; #pragma unroll
;       for (int i = 0; i < 2; i++)
; #pragma unroll
;         for (int j = 0; j < 2; j++) {
;           const int cl = wn * 64 + j * 32 + (lane & 31);
; #pragma unroll
;           for (int e = 0; e < 16; e++) {
;             const float v = acc[i][j][e];
;             const int rl = wm * 64 + i * 32 + rowmap(e, lane);
;             T[rl * 136 + cl] = f2bf(act ? siluf_(v) : v);
	v_add_f32_e32 v97, 1.0, v97
	v_add_f32_e32 v98, 1.0, v98
	v_add_f32_e32 v99, 1.0, v99
	v_add_f32_e32 v100, 1.0, v100
	v_add_f32_e32 v101, 1.0, v101
	v_rcp_f32_e32 v94, v94
	v_rcp_f32_e32 v95, v95
	v_rcp_f32_e32 v96, v96
	v_rcp_f32_e32 v97, v97
	v_rcp_f32_e32 v98, v98
	v_rcp_f32_e32 v99, v99
	v_rcp_f32_e32 v100, v100
	v_rcp_f32_e32 v101, v101
	v_mul_f32_e32 v86, v86, v94
	v_mul_f32_e32 v87, v87, v95
	v_mul_f32_e32 v88, v88, v96
	v_mul_f32_e32 v89, v89, v97
	v_mul_f32_e32 v90, v90, v98
	v_mul_f32_e32 v91, v91, v99
	v_mul_f32_e32 v92, v92, v100
	v_mul_f32_e32 v93, v93, v101
	v_cvt_pk_bf16_f32 v86, v86, v86
	v_cvt_pk_bf16_f32 v87, v87, v87
	v_cvt_pk_bf16_f32 v88, v88, v88
	v_cvt_pk_bf16_f32 v89, v89, v89
	v_cvt_pk_bf16_f32 v90, v90, v90
	v_cvt_pk_bf16_f32 v91, v91, v91
	v_cvt_pk_bf16_f32 v92, v92, v92
	v_cvt_pk_bf16_f32 v93, v93, v93
	ds_write_b16 v251, v86
	ds_write_b16 v251, v87 offset:272
	ds_write_b16 v251, v88 offset:544
	ds_write_b16 v251, v89 offset:816
	ds_write_b16 v252, v90
	ds_write_b16 v252, v91 offset:272
	ds_write_b16 v252, v92 offset:544
	ds_write_b16 v252, v93 offset:816
	v_accvgpr_read_b32 v86, a32
	v_accvgpr_read_b32 v87, a33
	v_accvgpr_read_b32 v88, a34
	v_accvgpr_read_b32 v89, a35
	v_accvgpr_read_b32 v90, a36
	v_accvgpr_read_b32 v91, a37
	v_accvgpr_read_b32 v92, a38
	v_accvgpr_read_b32 v93, a39
	v_mul_f32_e32 v94, 0xbfb8aa3b, v86
	v_mul_f32_e32 v95, 0xbfb8aa3b, v87
	v_mul_f32_e32 v96, 0xbfb8aa3b, v88
	v_mul_f32_e32 v97, 0xbfb8aa3b, v89
	v_mul_f32_e32 v98, 0xbfb8aa3b, v90
	v_mul_f32_e32 v99, 0xbfb8aa3b, v91
	v_mul_f32_e32 v100, 0xbfb8aa3b, v92
	v_mul_f32_e32 v101, 0xbfb8aa3b, v93
	v_exp_f32_e32 v94, v94
	v_exp_f32_e32 v95, v95
	v_exp_f32_e32 v96, v96
	v_exp_f32_e32 v97, v97
	v_exp_f32_e32 v98, v98
	v_exp_f32_e32 v99, v99
	v_exp_f32_e32 v100, v100
	v_exp_f32_e32 v101, v101
	v_add_f32_e32 v94, 1.0, v94
	v_add_f32_e32 v95, 1.0, v95
	v_add_f32_e32 v96, 1.0, v96
	v_add_f32_e32 v97, 1.0, v97
	v_add_f32_e32 v98, 1.0, v98
	v_add_f32_e32 v99, 1.0, v99
	v_add_f32_e32 v100, 1.0, v100
	v_add_f32_e32 v101, 1.0, v101
	v_rcp_f32_e32 v94, v94
	v_rcp_f32_e32 v95, v95
	v_rcp_f32_e32 v96, v96
	v_rcp_f32_e32 v97, v97
	v_rcp_f32_e32 v98, v98
	v_rcp_f32_e32 v99, v99
	v_rcp_f32_e32 v100, v100
	v_rcp_f32_e32 v101, v101
	v_mul_f32_e32 v86, v86, v94
	v_mul_f32_e32 v87, v87, v95
	v_mul_f32_e32 v88, v88, v96
	v_mul_f32_e32 v89, v89, v97
	v_mul_f32_e32 v90, v90, v98
	v_mul_f32_e32 v91, v91, v99
	v_mul_f32_e32 v92, v92, v100
	v_mul_f32_e32 v93, v93, v101
	v_cvt_pk_bf16_f32 v86, v86, v86
	v_cvt_pk_bf16_f32 v87, v87, v87
	v_cvt_pk_bf16_f32 v88, v88, v88
	v_cvt_pk_bf16_f32 v89, v89, v89
	v_cvt_pk_bf16_f32 v90, v90, v90
	v_cvt_pk_bf16_f32 v91, v91, v91
	v_cvt_pk_bf16_f32 v92, v92, v92
	v_cvt_pk_bf16_f32 v93, v93, v93
	ds_write_b16 v249, v86 offset:64
	ds_write_b16 v249, v87 offset:336
	ds_write_b16 v249, v88 offset:608
	ds_write_b16 v249, v89 offset:880
	ds_write_b16 v250, v90 offset:64
	ds_write_b16 v250, v91 offset:336
	ds_write_b16 v250, v92 offset:608
	ds_write_b16 v250, v93 offset:880
	v_accvgpr_read_b32 v86, a40
	v_accvgpr_read_b32 v87, a41
	v_accvgpr_read_b32 v88, a42
	v_accvgpr_read_b32 v89, a43
	v_accvgpr_read_b32 v90, a44
	v_accvgpr_read_b32 v91, a45
	v_accvgpr_read_b32 v92, a46
	v_accvgpr_read_b32 v93, a47
	v_mul_f32_e32 v94, 0xbfb8aa3b, v86
	v_mul_f32_e32 v95, 0xbfb8aa3b, v87
	v_mul_f32_e32 v96, 0xbfb8aa3b, v88
	v_mul_f32_e32 v97, 0xbfb8aa3b, v89
	v_mul_f32_e32 v98, 0xbfb8aa3b, v90
	v_mul_f32_e32 v99, 0xbfb8aa3b, v91
	v_mul_f32_e32 v100, 0xbfb8aa3b, v92
	v_mul_f32_e32 v101, 0xbfb8aa3b, v93
	v_exp_f32_e32 v94, v94
	v_exp_f32_e32 v95, v95
	v_exp_f32_e32 v96, v96
	v_exp_f32_e32 v97, v97
	v_exp_f32_e32 v98, v98
	v_exp_f32_e32 v99, v99
	v_exp_f32_e32 v100, v100
	v_exp_f32_e32 v101, v101
	v_add_f32_e32 v94, 1.0, v94
	v_add_f32_e32 v95, 1.0, v95
	v_add_f32_e32 v96, 1.0, v96
	v_add_f32_e32 v97, 1.0, v97
	v_add_f32_e32 v98, 1.0, v98
	v_add_f32_e32 v99, 1.0, v99
	v_add_f32_e32 v100, 1.0, v100
	v_add_f32_e32 v101, 1.0, v101
	v_rcp_f32_e32 v94, v94
	v_rcp_f32_e32 v95, v95
	v_rcp_f32_e32 v96, v96
	v_rcp_f32_e32 v97, v97
	v_rcp_f32_e32 v98, v98
	v_rcp_f32_e32 v99, v99
	v_rcp_f32_e32 v100, v100
	v_rcp_f32_e32 v101, v101
	v_mul_f32_e32 v86, v86, v94
	v_mul_f32_e32 v87, v87, v95
	v_mul_f32_e32 v88, v88, v96
	v_mul_f32_e32 v89, v89, v97
	v_mul_f32_e32 v90, v90, v98
	v_mul_f32_e32 v91, v91, v99
	v_mul_f32_e32 v92, v92, v100
	v_mul_f32_e32 v93, v93, v101
	v_cvt_pk_bf16_f32 v86, v86, v86
	v_cvt_pk_bf16_f32 v87, v87, v87
	v_cvt_pk_bf16_f32 v88, v88, v88
	v_cvt_pk_bf16_f32 v89, v89, v89
	v_cvt_pk_bf16_f32 v90, v90, v90
	v_cvt_pk_bf16_f32 v91, v91, v91
	v_cvt_pk_bf16_f32 v92, v92, v92
	v_cvt_pk_bf16_f32 v93, v93, v93
	ds_write_b16 v251, v86 offset:64
	ds_write_b16 v251, v87 offset:336
	ds_write_b16 v251, v88 offset:608
	ds_write_b16 v251, v89 offset:880
	ds_write_b16 v252, v90 offset:64
	ds_write_b16 v252, v91 offset:336
	ds_write_b16 v252, v92 offset:608
	ds_write_b16 v252, v93 offset:880
	v_accvgpr_read_b32 v86, a16
	v_accvgpr_read_b32 v87, a17
	v_accvgpr_read_b32 v88, a18
	v_accvgpr_read_b32 v89, a19
	v_accvgpr_read_b32 v90, a20
	v_accvgpr_read_b32 v91, a21
	v_accvgpr_read_b32 v92, a22
	v_accvgpr_read_b32 v93, a23
	v_mul_f32_e32 v94, 0xbfb8aa3b, v86
	v_mul_f32_e32 v95, 0xbfb8aa3b, v87
	v_mul_f32_e32 v96, 0xbfb8aa3b, v88
	v_mul_f32_e32 v97, 0xbfb8aa3b, v89
	v_mul_f32_e32 v98, 0xbfb8aa3b, v90
	v_mul_f32_e32 v99, 0xbfb8aa3b, v91
	v_mul_f32_e32 v100, 0xbfb8aa3b, v92
	v_mul_f32_e32 v101, 0xbfb8aa3b, v93
	v_exp_f32_e32 v94, v94
	v_exp_f32_e32 v95, v95
	v_exp_f32_e32 v96, v96
	v_exp_f32_e32 v97, v97
	v_exp_f32_e32 v98, v98
	v_exp_f32_e32 v99, v99
	v_exp_f32_e32 v100, v100
; __device__ __forceinline__ u16 f2bf(float f) { return (u16)(pack2(f, f) & 0xffffu); }
; __device__ __forceinline__ float siluf_(float x) { return x * __builtin_amdgcn_rcpf(1.f + __expf(-x)); }
; __device__ __forceinline__ int rowmap(int e, int lane) { return (e & 3) + 8 * (e >> 2) + 4 * (lane >> 5); }
; __device__ __forceinline__ void phase1(const Params& p, char* smem) {
;     ...
;       u16* T = (u16*)smem;
;       const bool act = (seg == 0 || seg == 3 || seg == 7);
; #pragma unroll
;       for (int i = 0; i < 2; i++)
; #pragma unroll
;         for (int j = 0; j < 2; j++) {
;           const int cl = wn * 64 + j * 32 + (lane & 31);
; #pragma unroll
;           for (int e = 0; e < 16; e++) {
;             const float v = acc[i][j][e];
;             const int rl = wm * 64 + i * 32 + rowmap(e, lane);
;             T[rl * 136 + cl] = f2bf(act ? siluf_(v) : v);
	v_exp_f32_e32 v101, v101
	v_add_f32_e32 v94, 1.0, v94
	v_add_f32_e32 v95, 1.0, v95
	v_add_f32_e32 v96, 1.0, v96
	v_add_f32_e32 v97, 1.0, v97
	v_add_f32_e32 v98, 1.0, v98
	v_add_f32_e32 v99, 1.0, v99
	v_add_f32_e32 v100, 1.0, v100
	v_add_f32_e32 v101, 1.0, v101
	v_rcp_f32_e32 v94, v94
	v_rcp_f32_e32 v95, v95
	v_rcp_f32_e32 v96, v96
	v_rcp_f32_e32 v97, v97
	v_rcp_f32_e32 v98, v98
	v_rcp_f32_e32 v99, v99
	v_rcp_f32_e32 v100, v100
	v_rcp_f32_e32 v101, v101
	v_mul_f32_e32 v86, v86, v94
	v_mul_f32_e32 v87, v87, v95
	v_mul_f32_e32 v88, v88, v96
	v_mul_f32_e32 v89, v89, v97
	v_mul_f32_e32 v90, v90, v98
	v_mul_f32_e32 v91, v91, v99
	v_mul_f32_e32 v92, v92, v100
	v_mul_f32_e32 v93, v93, v101
	v_cvt_pk_bf16_f32 v86, v86, v86
	v_cvt_pk_bf16_f32 v87, v87, v87
	v_cvt_pk_bf16_f32 v88, v88, v88
	v_cvt_pk_bf16_f32 v89, v89, v89
	v_cvt_pk_bf16_f32 v90, v90, v90
	v_cvt_pk_bf16_f32 v91, v91, v91
	v_cvt_pk_bf16_f32 v92, v92, v92
	v_cvt_pk_bf16_f32 v93, v93, v93
	ds_write_b16 v253, v86
	ds_write_b16 v253, v87 offset:272
	ds_write_b16 v253, v88 offset:544
	ds_write_b16 v253, v89 offset:816
	ds_write_b16 v214, v90
	ds_write_b16 v214, v91 offset:272
	ds_write_b16 v214, v92 offset:544
	ds_write_b16 v214, v93 offset:816
	v_accvgpr_read_b32 v86, a24
	v_accvgpr_read_b32 v87, a25
	v_accvgpr_read_b32 v88, a26
	v_accvgpr_read_b32 v89, a27
	v_accvgpr_read_b32 v90, a28
	v_accvgpr_read_b32 v91, a29
	v_accvgpr_read_b32 v92, a30
	v_accvgpr_read_b32 v93, a31
	v_mul_f32_e32 v94, 0xbfb8aa3b, v86
	v_mul_f32_e32 v95, 0xbfb8aa3b, v87
	v_mul_f32_e32 v96, 0xbfb8aa3b, v88
	v_mul_f32_e32 v97, 0xbfb8aa3b, v89
	v_mul_f32_e32 v98, 0xbfb8aa3b, v90
	v_mul_f32_e32 v99, 0xbfb8aa3b, v91
	v_mul_f32_e32 v100, 0xbfb8aa3b, v92
	v_mul_f32_e32 v101, 0xbfb8aa3b, v93
	v_exp_f32_e32 v94, v94
	v_exp_f32_e32 v95, v95
	v_exp_f32_e32 v96, v96
	v_exp_f32_e32 v97, v97
	v_exp_f32_e32 v98, v98
	v_exp_f32_e32 v99, v99
	v_exp_f32_e32 v100, v100
	v_exp_f32_e32 v101, v101
	v_add_f32_e32 v94, 1.0, v94
	v_add_f32_e32 v95, 1.0, v95
	v_add_f32_e32 v96, 1.0, v96
	v_add_f32_e32 v97, 1.0, v97
	v_add_f32_e32 v98, 1.0, v98
	v_add_f32_e32 v99, 1.0, v99
	v_add_f32_e32 v100, 1.0, v100
	v_add_f32_e32 v101, 1.0, v101
	v_rcp_f32_e32 v94, v94
	v_rcp_f32_e32 v95, v95
	v_rcp_f32_e32 v96, v96
	v_rcp_f32_e32 v97, v97
	v_rcp_f32_e32 v98, v98
	v_rcp_f32_e32 v99, v99
	v_rcp_f32_e32 v100, v100
	v_rcp_f32_e32 v101, v101
	v_mul_f32_e32 v86, v86, v94
	v_mul_f32_e32 v87, v87, v95
	v_mul_f32_e32 v88, v88, v96
	v_mul_f32_e32 v89, v89, v97
	v_mul_f32_e32 v90, v90, v98
	v_mul_f32_e32 v91, v91, v99
	v_mul_f32_e32 v92, v92, v100
	v_mul_f32_e32 v93, v93, v101
	v_cvt_pk_bf16_f32 v86, v86, v86
	v_cvt_pk_bf16_f32 v87, v87, v87
	v_cvt_pk_bf16_f32 v88, v88, v88
	v_cvt_pk_bf16_f32 v89, v89, v89
	v_cvt_pk_bf16_f32 v90, v90, v90
	v_cvt_pk_bf16_f32 v91, v91, v91
	v_cvt_pk_bf16_f32 v92, v92, v92
	v_cvt_pk_bf16_f32 v93, v93, v93
	ds_write_b16 v216, v86
	ds_write_b16 v216, v87 offset:272
	ds_write_b16 v216, v88 offset:544
	ds_write_b16 v216, v89 offset:816
	ds_write_b16 v218, v90
	ds_write_b16 v218, v91 offset:272
	ds_write_b16 v218, v92 offset:544
	ds_write_b16 v218, v93 offset:816
	v_accvgpr_read_b32 v86, a0
	v_accvgpr_read_b32 v87, a1
	v_accvgpr_read_b32 v88, a2
	v_accvgpr_read_b32 v89, a3
	v_accvgpr_read_b32 v90, a4
	v_accvgpr_read_b32 v91, a5
	v_accvgpr_read_b32 v92, a6
	v_accvgpr_read_b32 v93, a7
	v_mul_f32_e32 v94, 0xbfb8aa3b, v86
	v_mul_f32_e32 v95, 0xbfb8aa3b, v87
	v_mul_f32_e32 v96, 0xbfb8aa3b, v88
	v_mul_f32_e32 v97, 0xbfb8aa3b, v89
	v_mul_f32_e32 v98, 0xbfb8aa3b, v90
	v_mul_f32_e32 v99, 0xbfb8aa3b, v91
	v_mul_f32_e32 v100, 0xbfb8aa3b, v92
	v_mul_f32_e32 v101, 0xbfb8aa3b, v93
	v_exp_f32_e32 v94, v94
	v_exp_f32_e32 v95, v95
	v_exp_f32_e32 v96, v96
	v_exp_f32_e32 v97, v97
	v_exp_f32_e32 v98, v98
	v_exp_f32_e32 v99, v99
	v_exp_f32_e32 v100, v100
	v_exp_f32_e32 v101, v101
	v_add_f32_e32 v94, 1.0, v94
	v_add_f32_e32 v95, 1.0, v95
	v_add_f32_e32 v96, 1.0, v96
	v_add_f32_e32 v97, 1.0, v97
	v_add_f32_e32 v98, 1.0, v98
	v_add_f32_e32 v99, 1.0, v99
	v_add_f32_e32 v100, 1.0, v100
	v_add_f32_e32 v101, 1.0, v101
	v_rcp_f32_e32 v94, v94
	v_rcp_f32_e32 v95, v95
	v_rcp_f32_e32 v96, v96
	v_rcp_f32_e32 v97, v97
	v_rcp_f32_e32 v98, v98
	v_rcp_f32_e32 v99, v99
	v_rcp_f32_e32 v100, v100
	v_rcp_f32_e32 v101, v101
	v_mul_f32_e32 v86, v86, v94
	v_mul_f32_e32 v87, v87, v95
	v_mul_f32_e32 v88, v88, v96
	v_mul_f32_e32 v89, v89, v97
	v_mul_f32_e32 v90, v90, v98
	v_mul_f32_e32 v91, v91, v99
	v_mul_f32_e32 v92, v92, v100
	v_mul_f32_e32 v93, v93, v101
	v_cvt_pk_bf16_f32 v86, v86, v86
	v_cvt_pk_bf16_f32 v87, v87, v87
	v_cvt_pk_bf16_f32 v88, v88, v88
	v_cvt_pk_bf16_f32 v89, v89, v89
	v_cvt_pk_bf16_f32 v90, v90, v90
	v_cvt_pk_bf16_f32 v91, v91, v91
	v_cvt_pk_bf16_f32 v92, v92, v92
	v_cvt_pk_bf16_f32 v93, v93, v93
	ds_write_b16 v253, v86 offset:64
	ds_write_b16 v253, v87 offset:336
	ds_write_b16 v253, v88 offset:608
	ds_write_b16 v253, v89 offset:880
	ds_write_b16 v214, v90 offset:64
	ds_write_b16 v214, v91 offset:336
	ds_write_b16 v214, v92 offset:608
	ds_write_b16 v214, v93 offset:880
	v_accvgpr_read_b32 v86, a8
	v_accvgpr_read_b32 v87, a9
	v_accvgpr_read_b32 v88, a10
	v_accvgpr_read_b32 v89, a11
	v_accvgpr_read_b32 v90, a12
	v_accvgpr_read_b32 v91, a13
	v_accvgpr_read_b32 v92, a14
	v_accvgpr_read_b32 v93, a15
	v_mul_f32_e32 v94, 0xbfb8aa3b, v86
	v_mul_f32_e32 v95, 0xbfb8aa3b, v87
	v_mul_f32_e32 v96, 0xbfb8aa3b, v88
	v_mul_f32_e32 v97, 0xbfb8aa3b, v89
	v_mul_f32_e32 v98, 0xbfb8aa3b, v90
	v_mul_f32_e32 v99, 0xbfb8aa3b, v91
	v_mul_f32_e32 v100, 0xbfb8aa3b, v92
	v_mul_f32_e32 v101, 0xbfb8aa3b, v93
	v_exp_f32_e32 v94, v94
	v_exp_f32_e32 v95, v95
	v_exp_f32_e32 v96, v96
	v_exp_f32_e32 v97, v97
	v_exp_f32_e32 v98, v98
	v_exp_f32_e32 v99, v99
	v_exp_f32_e32 v100, v100
	v_exp_f32_e32 v101, v101
	v_add_f32_e32 v94, 1.0, v94
	v_add_f32_e32 v95, 1.0, v95
	v_add_f32_e32 v96, 1.0, v96
	v_add_f32_e32 v97, 1.0, v97
	v_add_f32_e32 v98, 1.0, v98
	v_add_f32_e32 v99, 1.0, v99
	v_add_f32_e32 v100, 1.0, v100
	v_add_f32_e32 v101, 1.0, v101
	v_rcp_f32_e32 v94, v94
	v_rcp_f32_e32 v95, v95
	v_rcp_f32_e32 v96, v96
	v_rcp_f32_e32 v97, v97
	v_rcp_f32_e32 v98, v98
	v_rcp_f32_e32 v99, v99
	v_rcp_f32_e32 v100, v100
	v_rcp_f32_e32 v101, v101
	v_mul_f32_e32 v86, v86, v94
	v_mul_f32_e32 v87, v87, v95
	v_mul_f32_e32 v88, v88, v96
	v_mul_f32_e32 v89, v89, v97
	v_mul_f32_e32 v90, v90, v98
	v_mul_f32_e32 v91, v91, v99
	v_mul_f32_e32 v92, v92, v100
	v_mul_f32_e32 v93, v93, v101
	v_cvt_pk_bf16_f32 v86, v86, v86
	v_cvt_pk_bf16_f32 v87, v87, v87
	v_cvt_pk_bf16_f32 v88, v88, v88
	v_cvt_pk_bf16_f32 v89, v89, v89
	v_cvt_pk_bf16_f32 v90, v90, v90
	v_cvt_pk_bf16_f32 v91, v91, v91
	v_cvt_pk_bf16_f32 v92, v92, v92
	v_cvt_pk_bf16_f32 v93, v93, v93
	ds_write_b16 v216, v86 offset:64
	ds_write_b16 v216, v87 offset:336
	ds_write_b16 v216, v88 offset:608
	ds_write_b16 v216, v89 offset:880
	ds_write_b16 v218, v90 offset:64
	ds_write_b16 v218, v91 offset:336
	ds_write_b16 v218, v92 offset:608
	ds_write_b16 v218, v93 offset:880
; __device__ __forceinline__ u16 f2bf(float f) { return (u16)(pack2(f, f) & 0xffffu); }
; __device__ __forceinline__ float siluf_(float x) { return x * __builtin_amdgcn_rcpf(1.f + __expf(-x)); }
; __device__ __forceinline__ int rowmap(int e, int lane) { return (e & 3) + 8 * (e >> 2) + 4 * (lane >> 5); }
; __device__ __forceinline__ void phase1(const Params& p, char* smem) {
;     ...
;       u16* T = (u16*)smem;
;       const bool act = (seg == 0 || seg == 3 || seg == 7);
; #pragma unroll
;       for (int i = 0; i < 2; i++)
; #pragma unroll
;         for (int j = 0; j < 2; j++) {
;           const int cl = wn * 64 + j * 32 + (lane & 31);
; #pragma unroll
;           for (int e = 0; e < 16; e++) {
;             const float v = acc[i][j][e];
;             const int rl = wm * 64 + i * 32 + rowmap(e, lane);
;             T[rl * 136 + cl] = f2bf(act ? siluf_(v) : v);
;             if (seg >= 4 && seg <= 6) {
;               const int row = m0 + rl; const int ch = (seg - 4) * 512 + cb + cl;
;               if (row < NTP) { int t = row & 2047; if (t >= 2045) p.out[OUT_CP + ((size_t)(row >> 11) * 3 + (t - 2045)) * 1536 + ch] = v; }
;               else { int rs = row - NTP; int t = rs & 3; if (t >= 1) p.out[OUT_CS + ((size_t)(rs >> 2) * 3 + (t - 1)) * 1536 + ch] = v; }
;             }
;           }
;         }
;       __syncthreads();
;       u16* dst; int ld;
;       if (seg == 0) { dst = QA + cb; ld = 512; }
;       else if (seg == 2) { dst = VA + cb; ld = 512; }
;       else if (seg == 3) { dst = OGA + cb; ld = 512; }
;       else if (seg == 7) { dst = ZB + cb; ld = 512; }
;       else { dst = RAW + (seg - 4) * 512 + cb; ld = 1536; }
.Lp1_fast_done:
	s_lshl_b32 s36, s17, 9
	s_cmp_lt_u32 s6, 4
	s_cselect_b64 s[4:5], -1, 0
	s_branch .LBB0_702
.Lp1_generic:
	s_mov_b64 s[0:1], -1
	s_cmp_gt_u32 s6, 3
	s_cselect_b64 s[0:1], -1, 0
	s_cmp_lt_u32 s6, 4
	s_mov_b64 s[4:5], -1
	s_cbranch_scc1 .LBB0_181
	s_cmp_gt_i32 s17, 6
	s_cbranch_scc1 .LBB0_181
	s_cmp_eq_u32 s17, 3
	s_cselect_b64 s[4:5], -1, 0

; __device__ __forceinline__ void gdn_chunk_item(const Params& p, int item, char* smem) {
;     ...
;     u16* tile = (u16*)Xs;
;     for (int i = tid; i < 67 * 48; i += 256) {
;       const int row = i / 48, rem = i - row * 48, seg = rem >> 4, c8 = rem & 15;
;       uint4 v4 = make_uint4(0, 0, 0, 0);
;       if (n > 0 || row >= 3) v4 = *(const uint4*)(RAW + (size_t)(tok0 - 3 + row) * 1536 + seg * 512 + h * 128 + c8 * 8);
;       *(uint4*)&tile[row * 384 + seg * 128 + c8 * 8] = v4;
;     }
.LBB0_800:
	s_or_b64 exec, exec, s[0:1]
	s_waitcnt lgkmcnt(0)
	s_barrier
	ds_read_b32 v235, v35 offset:65276
	s_cmp_lg_u32 s3, 0
	s_cselect_b64 s[0:1], -1, 0
	s_add_i32 s3, s55, -3
	s_lshl_b32 s72, s6, 7
	s_mov_b64 s[6:7], 0
	s_movk_i32 s36, 0xffd0
	s_movk_i32 s56, 0xc00
	v_mov_b32_e32 v3, s3
	v_mov_b64_e32 v[4:5], s[78:79]
	v_mov_b32_e32 v7, 0
	s_nop 0
	v_mad_i64_i32 v[4:5], vcc, v3, s56, v[4:5]
	s_lshl_b32 s56, s72, 1
	v_lshl_add_u64 v[4:5], v[4:5], 0, s[56:57]
	v_lshl_add_u64 v[4:5], v[4:5], 0, v[34:35]
	v_mov_b32_e32 v0, v237
	v_mul_u32_u24_e32 v1, 0xaaab, v0
	v_lshrrev_b32_e32 v1, 21, v1
	v_mad_i32_i24 v2, v1, s36, v0
	v_ashrrev_i32_e32 v2, 4, v2
	v_mul_u32_u24_e32 v3, 0xc00, v1
	v_lshl_add_u32 v6, v2, 10, v3
	v_lshl_add_u64 v[2:3], v[4:5], 0, v[6:7]
	v_accvgpr_write_b32 a196, 0
	v_accvgpr_write_b32 a197, 0
	v_accvgpr_write_b32 a198, 0
	v_accvgpr_write_b32 a199, 0
	v_cmp_lt_u32_e32 vcc, 0x8f, v0
	s_nop 1
	s_or_b64 vcc, s[0:1], vcc
	s_and_saveexec_b64 s[36:37], vcc
	global_load_dwordx4 a[196:199], v[2:3], off
	s_or_b64 exec, exec, s[36:37]
	s_movk_i32 s36, 0xffd0
	v_add_u32_e32 v0, 256, v237
	v_mul_u32_u24_e32 v1, 0xaaab, v0
	v_lshrrev_b32_e32 v1, 21, v1
	v_mad_i32_i24 v2, v1, s36, v0
	v_ashrrev_i32_e32 v2, 4, v2
	v_mul_u32_u24_e32 v3, 0xc00, v1
	v_lshl_add_u32 v6, v2, 10, v3
	v_lshl_add_u64 v[2:3], v[4:5], 0, v[6:7]
	global_load_dwordx4 a[200:203], v[2:3], off
	v_add_u32_e32 v0, 512, v237
	v_mul_u32_u24_e32 v1, 0xaaab, v0
	v_lshrrev_b32_e32 v1, 21, v1
	v_mad_i32_i24 v2, v1, s36, v0
	v_ashrrev_i32_e32 v2, 4, v2
	v_mul_u32_u24_e32 v3, 0xc00, v1
	v_lshl_add_u32 v6, v2, 10, v3
	v_lshl_add_u64 v[2:3], v[4:5], 0, v[6:7]
	global_load_dwordx4 a[204:207], v[2:3], off
	v_add_u32_e32 v0, 768, v237
	v_mul_u32_u24_e32 v1, 0xaaab, v0
	v_lshrrev_b32_e32 v1, 21, v1
	v_mad_i32_i24 v2, v1, s36, v0
	v_ashrrev_i32_e32 v2, 4, v2
	v_mul_u32_u24_e32 v3, 0xc00, v1
	v_lshl_add_u32 v6, v2, 10, v3
	v_lshl_add_u64 v[2:3], v[4:5], 0, v[6:7]
	global_load_dwordx4 a[208:211], v[2:3], off
	v_add_u32_e32 v0, 1024, v237
	v_mul_u32_u24_e32 v1, 0xaaab, v0
	v_lshrrev_b32_e32 v1, 21, v1
	v_mad_i32_i24 v2, v1, s36, v0
	v_ashrrev_i32_e32 v2, 4, v2
	v_mul_u32_u24_e32 v3, 0xc00, v1
	v_lshl_add_u32 v6, v2, 10, v3
	v_lshl_add_u64 v[2:3], v[4:5], 0, v[6:7]
	global_load_dwordx4 a[212:215], v[2:3], off
	v_add_u32_e32 v0, 1280, v237
	v_mul_u32_u24_e32 v1, 0xaaab, v0
	v_lshrrev_b32_e32 v1, 21, v1
	v_mad_i32_i24 v2, v1, s36, v0
	v_ashrrev_i32_e32 v2, 4, v2
	v_mul_u32_u24_e32 v3, 0xc00, v1
	v_lshl_add_u32 v6, v2, 10, v3
	v_lshl_add_u64 v[2:3], v[4:5], 0, v[6:7]
	global_load_dwordx4 a[216:219], v[2:3], off
	v_add_u32_e32 v0, 1536, v237
	v_mul_u32_u24_e32 v1, 0xaaab, v0
	v_lshrrev_b32_e32 v1, 21, v1
	v_mad_i32_i24 v2, v1, s36, v0
	v_ashrrev_i32_e32 v2, 4, v2
	v_mul_u32_u24_e32 v3, 0xc00, v1
	v_lshl_add_u32 v6, v2, 10, v3
	v_lshl_add_u64 v[2:3], v[4:5], 0, v[6:7]
	global_load_dwordx4 a[220:223], v[2:3], off
	v_add_u32_e32 v0, 1792, v237
	v_mul_u32_u24_e32 v1, 0xaaab, v0
	v_lshrrev_b32_e32 v1, 21, v1
	v_mad_i32_i24 v2, v1, s36, v0
	v_ashrrev_i32_e32 v2, 4, v2
	v_mul_u32_u24_e32 v3, 0xc00, v1
	v_lshl_add_u32 v6, v2, 10, v3
	v_lshl_add_u64 v[2:3], v[4:5], 0, v[6:7]
	global_load_dwordx4 a[224:227], v[2:3], off
	v_add_u32_e32 v0, 2048, v237
	v_mul_u32_u24_e32 v1, 0xaaab, v0
	v_lshrrev_b32_e32 v1, 21, v1
	v_mad_i32_i24 v2, v1, s36, v0
	v_ashrrev_i32_e32 v2, 4, v2
	v_mul_u32_u24_e32 v3, 0xc00, v1
	v_lshl_add_u32 v6, v2, 10, v3
	v_lshl_add_u64 v[2:3], v[4:5], 0, v[6:7]
	global_load_dwordx4 a[228:231], v[2:3], off
	v_add_u32_e32 v0, 2304, v237
	v_mul_u32_u24_e32 v1, 0xaaab, v0
	v_lshrrev_b32_e32 v1, 21, v1
	v_mad_i32_i24 v2, v1, s36, v0
	v_ashrrev_i32_e32 v2, 4, v2
	v_mul_u32_u24_e32 v3, 0xc00, v1
	v_lshl_add_u32 v6, v2, 10, v3
	v_lshl_add_u64 v[2:3], v[4:5], 0, v[6:7]
	global_load_dwordx4 a[232:235], v[2:3], off
	v_add_u32_e32 v0, 2560, v237
	v_mul_u32_u24_e32 v1, 0xaaab, v0
	v_lshrrev_b32_e32 v1, 21, v1
	v_mad_i32_i24 v2, v1, s36, v0
	v_ashrrev_i32_e32 v2, 4, v2
	v_mul_u32_u24_e32 v3, 0xc00, v1
	v_lshl_add_u32 v6, v2, 10, v3
	v_lshl_add_u64 v[2:3], v[4:5], 0, v[6:7]
	global_load_dwordx4 a[236:239], v[2:3], off
	v_add_u32_e32 v0, 2816, v237
	v_mul_u32_u24_e32 v1, 0xaaab, v0
	v_lshrrev_b32_e32 v1, 21, v1
	v_mad_i32_i24 v2, v1, s36, v0
	v_ashrrev_i32_e32 v2, 4, v2
	v_mul_u32_u24_e32 v3, 0xc00, v1
	v_lshl_add_u32 v6, v2, 10, v3
	v_lshl_add_u64 v[2:3], v[4:5], 0, v[6:7]
	global_load_dwordx4 a[240:243], v[2:3], off
	v_add_u32_e32 v0, 3072, v237
	v_mul_u32_u24_e32 v1, 0xaaab, v0
	v_lshrrev_b32_e32 v1, 21, v1
	v_mad_i32_i24 v2, v1, s36, v0
	v_ashrrev_i32_e32 v2, 4, v2
	v_mul_u32_u24_e32 v3, 0xc00, v1
	v_lshl_add_u32 v6, v2, 10, v3
	v_lshl_add_u64 v[2:3], v[4:5], 0, v[6:7]
	v_cmp_gt_u32_e32 vcc, 0x90, v237
	s_nop 1
	s_and_saveexec_b64 s[36:37], vcc
	global_load_dwordx4 a[244:247], v[2:3], off
	s_or_b64 exec, exec, s[36:37]
	s_movk_i32 s36, 0xffd0
	v_lshlrev_b32_e32 v6, 4, v240
	s_waitcnt vmcnt(0)
; __device__ __forceinline__ void gdn_chunk_item(const Params& p, int item, char* smem) {
;     ...
;       if (n > 0 || row >= 3) v4 = *(const uint4*)(RAW + (size_t)(tok0 - 3 + row) * 1536 + seg * 512 + h * 128 + c8 * 8);
;       *(uint4*)&tile[row * 384 + seg * 128 + c8 * 8] = v4;
;     }
;     __syncthreads();
	v_mov_b32_e32 v0, v237
	v_mul_u32_u24_e32 v1, 0xaaab, v0
	v_lshrrev_b32_e32 v1, 21, v1
	v_mad_i32_i24 v2, v1, s36, v0
	v_ashrrev_i32_e32 v2, 4, v2
	v_lshlrev_b32_e32 v2, 8, v2
	v_mul_u32_u24_e32 v1, 0x300, v1
	v_add3_u32 v1, v1, v2, v6
	v_add_u32_e32 v1, 0x10400, v1
	ds_write_b128 v1, a[196:199]
	v_add_u32_e32 v0, 256, v237
	v_mul_u32_u24_e32 v1, 0xaaab, v0
	v_lshrrev_b32_e32 v1, 21, v1
	v_mad_i32_i24 v2, v1, s36, v0
	v_ashrrev_i32_e32 v2, 4, v2
	v_lshlrev_b32_e32 v2, 8, v2
	v_mul_u32_u24_e32 v1, 0x300, v1
	v_add3_u32 v1, v1, v2, v6
	v_add_u32_e32 v1, 0x10400, v1
	ds_write_b128 v1, a[200:203]
	v_add_u32_e32 v0, 512, v237
	v_mul_u32_u24_e32 v1, 0xaaab, v0
	v_lshrrev_b32_e32 v1, 21, v1
	v_mad_i32_i24 v2, v1, s36, v0
	v_ashrrev_i32_e32 v2, 4, v2
	v_lshlrev_b32_e32 v2, 8, v2
	v_mul_u32_u24_e32 v1, 0x300, v1
	v_add3_u32 v1, v1, v2, v6
	v_add_u32_e32 v1, 0x10400, v1
	ds_write_b128 v1, a[204:207]
	v_add_u32_e32 v0, 768, v237
	v_mul_u32_u24_e32 v1, 0xaaab, v0
	v_lshrrev_b32_e32 v1, 21, v1
	v_mad_i32_i24 v2, v1, s36, v0
	v_ashrrev_i32_e32 v2, 4, v2
	v_lshlrev_b32_e32 v2, 8, v2
	v_mul_u32_u24_e32 v1, 0x300, v1
	v_add3_u32 v1, v1, v2, v6
	v_add_u32_e32 v1, 0x10400, v1
	ds_write_b128 v1, a[208:211]
	v_add_u32_e32 v0, 1024, v237
	v_mul_u32_u24_e32 v1, 0xaaab, v0
	v_lshrrev_b32_e32 v1, 21, v1
	v_mad_i32_i24 v2, v1, s36, v0
	v_ashrrev_i32_e32 v2, 4, v2
	v_lshlrev_b32_e32 v2, 8, v2
	v_mul_u32_u24_e32 v1, 0x300, v1
	v_add3_u32 v1, v1, v2, v6
	v_add_u32_e32 v1, 0x10400, v1
	ds_write_b128 v1, a[212:215]
	v_add_u32_e32 v0, 1280, v237
	v_mul_u32_u24_e32 v1, 0xaaab, v0
	v_lshrrev_b32_e32 v1, 21, v1
	v_mad_i32_i24 v2, v1, s36, v0
	v_ashrrev_i32_e32 v2, 4, v2
	v_lshlrev_b32_e32 v2, 8, v2
	v_mul_u32_u24_e32 v1, 0x300, v1
	v_add3_u32 v1, v1, v2, v6
	v_add_u32_e32 v1, 0x10400, v1
	ds_write_b128 v1, a[216:219]
	v_add_u32_e32 v0, 1536, v237
	v_mul_u32_u24_e32 v1, 0xaaab, v0
	v_lshrrev_b32_e32 v1, 21, v1
	v_mad_i32_i24 v2, v1, s36, v0
	v_ashrrev_i32_e32 v2, 4, v2
	v_lshlrev_b32_e32 v2, 8, v2
	v_mul_u32_u24_e32 v1, 0x300, v1
	v_add3_u32 v1, v1, v2, v6
	v_add_u32_e32 v1, 0x10400, v1
	ds_write_b128 v1, a[220:223]
	v_add_u32_e32 v0, 1792, v237
	v_mul_u32_u24_e32 v1, 0xaaab, v0
	v_lshrrev_b32_e32 v1, 21, v1
	v_mad_i32_i24 v2, v1, s36, v0
	v_ashrrev_i32_e32 v2, 4, v2
	v_lshlrev_b32_e32 v2, 8, v2
	v_mul_u32_u24_e32 v1, 0x300, v1
	v_add3_u32 v1, v1, v2, v6
	v_add_u32_e32 v1, 0x10400, v1
	ds_write_b128 v1, a[224:227]
	v_add_u32_e32 v0, 2048, v237
	v_mul_u32_u24_e32 v1, 0xaaab, v0
	v_lshrrev_b32_e32 v1, 21, v1
	v_mad_i32_i24 v2, v1, s36, v0
	v_ashrrev_i32_e32 v2, 4, v2
	v_lshlrev_b32_e32 v2, 8, v2
	v_mul_u32_u24_e32 v1, 0x300, v1
	v_add3_u32 v1, v1, v2, v6
	v_add_u32_e32 v1, 0x10400, v1
	ds_write_b128 v1, a[228:231]
	v_add_u32_e32 v0, 2304, v237
	v_mul_u32_u24_e32 v1, 0xaaab, v0
	v_lshrrev_b32_e32 v1, 21, v1
	v_mad_i32_i24 v2, v1, s36, v0
	v_ashrrev_i32_e32 v2, 4, v2
	v_lshlrev_b32_e32 v2, 8, v2
	v_mul_u32_u24_e32 v1, 0x300, v1
	v_add3_u32 v1, v1, v2, v6
	v_add_u32_e32 v1, 0x10400, v1
	ds_write_b128 v1, a[232:235]
	v_add_u32_e32 v0, 2560, v237
	v_mul_u32_u24_e32 v1, 0xaaab, v0
	v_lshrrev_b32_e32 v1, 21, v1
	v_mad_i32_i24 v2, v1, s36, v0
	v_ashrrev_i32_e32 v2, 4, v2
	v_lshlrev_b32_e32 v2, 8, v2
	v_mul_u32_u24_e32 v1, 0x300, v1
	v_add3_u32 v1, v1, v2, v6
	v_add_u32_e32 v1, 0x10400, v1
	ds_write_b128 v1, a[236:239]
	v_add_u32_e32 v0, 2816, v237
	v_mul_u32_u24_e32 v1, 0xaaab, v0
	v_lshrrev_b32_e32 v1, 21, v1
	v_mad_i32_i24 v2, v1, s36, v0
	v_ashrrev_i32_e32 v2, 4, v2
	v_lshlrev_b32_e32 v2, 8, v2
	v_mul_u32_u24_e32 v1, 0x300, v1
	v_add3_u32 v1, v1, v2, v6
	v_add_u32_e32 v1, 0x10400, v1
	ds_write_b128 v1, a[240:243]
	v_add_u32_e32 v0, 3072, v237
	v_mul_u32_u24_e32 v1, 0xaaab, v0
	v_lshrrev_b32_e32 v1, 21, v1
	v_mad_i32_i24 v2, v1, s36, v0
	v_ashrrev_i32_e32 v2, 4, v2
	v_lshlrev_b32_e32 v2, 8, v2
	v_mul_u32_u24_e32 v1, 0x300, v1
	v_add3_u32 v1, v1, v2, v6
	v_add_u32_e32 v1, 0x10400, v1
	v_cmp_gt_u32_e32 vcc, 0x90, v237
	s_nop 1
	s_and_saveexec_b64 s[36:37], vcc
	ds_write_b128 v1, a[244:247]
	s_or_b64 exec, exec, s[36:37]
	s_mov_b64 s[6:7], exec

; __device__ __forceinline__ u16 f2bf(float f) { return (u16)(pack2(f, f) & 0xffffu); }
; __device__ __forceinline__ float bf2f(u16 h) { return __uint_as_float(((unsigned)h) << 16); }
; __device__ __forceinline__ float sum32(float v) { v = dpp_row_sum16(v); v += __shfl_xor(v, 16); return v; }
; __device__ __forceinline__ int rowmap(int e, int lane) { return (e & 3) + 8 * (e >> 2) + 4 * (lane >> 5); }
; __device__ __forceinline__ void seq_item(const Params& p, int item, char* smem, const bool write_o = true) {
;     ...
;   for (int n = 0; n < 32; n++) {
; #pragma unroll
;     for (int e = 0; e < 16; e++) STs[rowmap(e, lane) * 136 + dcol] = f2bf(S[e]);
;     *(uint4*)&VTs[(tid >> 3) * 72 + (tid & 7) * 8] = vt4;
;     __syncthreads();
;     const int tok0 = b * 2048 + n * 64;
;     if (w < 2) {
;       f32x16 o;
; #pragma unroll
;       for (int e = 0; e < 16; e++) o[e] = bf2f(o0[e]);
; #pragma unroll
;       for (int ks = 0; ks < 8; ks++) {
;         bf16x8 bb = *(const bf16x8*)&STs[r * 136 + ks * 16 + hh];
;         o = mfma16(qbf[ks], bb, o);
;       }
; #pragma unroll
;       for (int e = 0; e < 16; e++) {
;         const int t = w * 32 + rowmap(e, lane);
;         if (write_o) Om[(size_t)(tok0 + t) * 512 + h * 128 + sl * 32 + r] = f2bf(o[e]);
;         float sq = sum32(o[e] * o[e]);
;         if (r == 0) SSQO[((size_t)(tok0 + t) * 4 + h) * 4 + sl] = sq;
;       }
.LBB0_1022:
	s_nop 0
	v_accvgpr_read_b32 v17, a15
	v_accvgpr_read_b32 v2, a0
	v_accvgpr_read_b32 v3, a1
	v_cvt_pk_bf16_f32 v0, v2, s0
	v_accvgpr_read_b32 v4, a2
	ds_write_b16 v82, v0
	v_cvt_pk_bf16_f32 v0, v3, s0
	v_accvgpr_read_b32 v5, a3
	ds_write_b16 v82, v0 offset:272
	v_cvt_pk_bf16_f32 v0, v4, s0
	v_accvgpr_read_b32 v6, a4
	ds_write_b16 v82, v0 offset:544
	v_cvt_pk_bf16_f32 v0, v5, s0
	v_accvgpr_read_b32 v7, a5
	ds_write_b16 v82, v0 offset:816
	v_cvt_pk_bf16_f32 v0, v6, s0
	v_accvgpr_read_b32 v8, a6
	ds_write_b16 v82, v0 offset:2176
	v_cvt_pk_bf16_f32 v0, v7, s0
	v_accvgpr_read_b32 v9, a7
	ds_write_b16 v82, v0 offset:2448
	v_cvt_pk_bf16_f32 v0, v8, s0
	v_accvgpr_read_b32 v10, a8
	ds_write_b16 v82, v0 offset:2720
	v_cvt_pk_bf16_f32 v0, v9, s0
	v_accvgpr_read_b32 v11, a9
	ds_write_b16 v82, v0 offset:2992
	v_cvt_pk_bf16_f32 v0, v10, s0
	v_accvgpr_read_b32 v12, a10
	ds_write_b16 v82, v0 offset:4352
	v_cvt_pk_bf16_f32 v0, v11, s0
	v_accvgpr_read_b32 v13, a11
	ds_write_b16 v82, v0 offset:4624
	v_cvt_pk_bf16_f32 v0, v12, s0
	v_accvgpr_read_b32 v14, a12
	ds_write_b16 v82, v0 offset:4896
	v_cvt_pk_bf16_f32 v0, v13, s0
	v_accvgpr_read_b32 v15, a13
	ds_write_b16 v82, v0 offset:5168
	v_cvt_pk_bf16_f32 v0, v14, s0
	v_accvgpr_read_b32 v16, a14
	ds_write_b16 v82, v0 offset:6528
	v_cvt_pk_bf16_f32 v0, v15, s0
	ds_write_b16 v82, v0 offset:6800
	v_cvt_pk_bf16_f32 v0, v16, s0
	ds_write_b16 v82, v0 offset:7072
	v_cvt_pk_bf16_f32 v0, v17, s0
	ds_write_b16 v82, v0 offset:7344
	s_waitcnt vmcnt(5)
	ds_write_b128 v59, v[102:105] offset:8704
	s_waitcnt lgkmcnt(0)
	s_barrier
	s_and_saveexec_b64 s[0:1], s[4:5]
	s_cbranch_execz .LBB0_1055
	ds_read_b128 v[18:21], v83
	ds_read_b128 v[22:25], v83 offset:32
	v_lshlrev_b32_e32 v0, 16, v57
	v_lshlrev_b32_e32 v26, 16, v61
	v_lshlrev_b32_e32 v27, 16, v87
	v_lshlrev_b32_e32 v28, 16, v88
	v_lshlrev_b32_e32 v29, 16, v89
	v_lshlrev_b32_e32 v30, 16, v90
	v_lshlrev_b32_e32 v31, 16, v91
	v_lshlrev_b32_e32 v32, 16, v92
	v_lshlrev_b32_e32 v33, 16, v93
	v_lshlrev_b32_e32 v63, 16, v94
	v_lshlrev_b32_e32 v65, 16, v95
	s_waitcnt vmcnt(4)
	v_lshlrev_b32_e32 v78, 16, v96
	s_waitcnt vmcnt(3)
	v_lshlrev_b32_e32 v79, 16, v97
	s_waitcnt vmcnt(2)
	v_lshlrev_b32_e32 v101, 16, v98
	s_waitcnt vmcnt(1)
	v_lshlrev_b32_e32 v186, 16, v99
	s_waitcnt vmcnt(0)
	v_lshlrev_b32_e32 v187, 16, v100
	v_accvgpr_write_b32 a0, v0
	v_accvgpr_write_b32 a1, v26
	v_accvgpr_write_b32 a2, v27
	v_accvgpr_write_b32 a3, v28
	v_accvgpr_write_b32 a4, v29
	v_accvgpr_write_b32 a5, v30
	v_accvgpr_write_b32 a6, v31
	v_accvgpr_write_b32 a7, v32
	v_accvgpr_write_b32 a8, v33
	v_accvgpr_write_b32 a9, v63
	v_accvgpr_write_b32 a10, v65
	v_accvgpr_write_b32 a11, v78
	v_accvgpr_write_b32 a12, v79
	v_accvgpr_write_b32 a13, v101
	v_accvgpr_write_b32 a14, v186
	v_accvgpr_write_b32 a15, v187
	v_cmp_lt_i32_e32 vcc, v85, v86
	v_lshl_add_u64 v[78:79], v[72:73], 0, s[22:23]
	s_waitcnt lgkmcnt(1)
	v_mfma_f32_32x32x16_bf16 a[0:15], v[154:157], v[18:21], a[0:15]
	v_cndmask_b32_e32 v0, v84, v85, vcc
	v_lshlrev_b32_e32 v63, 2, v0
	s_waitcnt lgkmcnt(0)
	v_mfma_f32_32x32x16_bf16 a[0:15], v[158:161], v[22:25], a[0:15]
	ds_read_b128 v[18:21], v83 offset:64
	ds_read_b128 v[22:25], v83 offset:96
	s_waitcnt lgkmcnt(1)
	v_mfma_f32_32x32x16_bf16 a[0:15], v[162:165], v[18:21], a[0:15]
	s_waitcnt lgkmcnt(0)
	v_mfma_f32_32x32x16_bf16 a[0:15], v[166:169], v[22:25], a[0:15]
	ds_read_b128 v[18:21], v83 offset:128
	ds_read_b128 v[22:25], v83 offset:160
	s_waitcnt lgkmcnt(1)
	v_mfma_f32_32x32x16_bf16 a[0:15], v[170:173], v[18:21], a[0:15]
	s_waitcnt lgkmcnt(0)
	v_mfma_f32_32x32x16_bf16 a[0:15], v[174:177], v[22:25], a[0:15]
	ds_read_b128 v[18:21], v83 offset:192
	ds_read_b128 v[22:25], v83 offset:224
	s_waitcnt lgkmcnt(1)
	v_mfma_f32_32x32x16_bf16 a[0:15], v[178:181], v[18:21], a[0:15]
	v_add_co_u32_e32 v20, vcc, s35, v78
	s_nop 1
	v_addc_co_u32_e32 v21, vcc, 0, v79, vcc
	s_waitcnt lgkmcnt(0)
	v_mfma_f32_32x32x16_bf16 a[0:15], v[182:185], v[22:25], a[0:15]
	s_nop 11
	v_accvgpr_read_b32 v18, a0
	v_accvgpr_read_b32 v19, a1
	v_accvgpr_read_b32 v20, a2
	v_accvgpr_read_b32 v21, a3
	v_accvgpr_read_b32 v22, a4
	v_accvgpr_read_b32 v23, a5
	v_accvgpr_read_b32 v24, a6
	v_accvgpr_read_b32 v25, a7
	v_accvgpr_read_b32 v26, a8
	v_accvgpr_read_b32 v27, a9
	v_accvgpr_read_b32 v28, a10
	v_accvgpr_read_b32 v29, a11
	v_accvgpr_read_b32 v30, a12
	v_accvgpr_read_b32 v31, a13
	v_accvgpr_read_b32 v32, a14
	v_accvgpr_read_b32 v33, a15
	v_mul_f32_e32 v57, v18, v18
	v_mul_f32_e32 v61, v19, v19
	v_mul_f32_e32 v87, v20, v20
	v_mul_f32_e32 v88, v21, v21
	v_mul_f32_e32 v89, v22, v22
	v_mul_f32_e32 v90, v23, v23
	v_mul_f32_e32 v91, v24, v24
	v_mul_f32_e32 v92, v25, v25
	v_mul_f32_e32 v93, v26, v26
	v_mul_f32_e32 v94, v27, v27
	v_mul_f32_e32 v95, v28, v28
	v_mul_f32_e32 v96, v29, v29
	v_mul_f32_e32 v97, v30, v30
	v_mul_f32_e32 v98, v31, v31
	v_mul_f32_e32 v99, v32, v32
	v_mul_f32_e32 v100, v33, v33
	v_mov_b32_dpp v57, v57 quad_perm:[1,0,3,2] row_mask:0xf bank_mask:0xf bound_ctrl:1
	v_mov_b32_dpp v61, v61 quad_perm:[1,0,3,2] row_mask:0xf bank_mask:0xf bound_ctrl:1
	v_mov_b32_dpp v87, v87 quad_perm:[1,0,3,2] row_mask:0xf bank_mask:0xf bound_ctrl:1
	v_mov_b32_dpp v88, v88 quad_perm:[1,0,3,2] row_mask:0xf bank_mask:0xf bound_ctrl:1
	v_mov_b32_dpp v89, v89 quad_perm:[1,0,3,2] row_mask:0xf bank_mask:0xf bound_ctrl:1
	v_mov_b32_dpp v90, v90 quad_perm:[1,0,3,2] row_mask:0xf bank_mask:0xf bound_ctrl:1
	v_mov_b32_dpp v91, v91 quad_perm:[1,0,3,2] row_mask:0xf bank_mask:0xf bound_ctrl:1
	v_mov_b32_dpp v92, v92 quad_perm:[1,0,3,2] row_mask:0xf bank_mask:0xf bound_ctrl:1
	v_mov_b32_dpp v93, v93 quad_perm:[1,0,3,2] row_mask:0xf bank_mask:0xf bound_ctrl:1
; __device__ __forceinline__ u16 f2bf(float f) { return (u16)(pack2(f, f) & 0xffffu); }
; __device__ __forceinline__ int rowmap(int e, int lane) { return (e & 3) + 8 * (e >> 2) + 4 * (lane >> 5); }
; __device__ __forceinline__ float dpp_row_sum16(float v) {
;   v += __int_as_float(__builtin_amdgcn_update_dpp(0, __float_as_int(v), 0xB1, 0xF, 0xF, true));
;   v += __int_as_float(__builtin_amdgcn_update_dpp(0, __float_as_int(v), 0x4E, 0xF, 0xF, true));
;   v += __int_as_float(__builtin_amdgcn_update_dpp(0, __float_as_int(v), 0x141, 0xF, 0xF, true));
;   v += __int_as_float(__builtin_amdgcn_update_dpp(0, __float_as_int(v), 0x140, 0xF, 0xF, true));
;   return v;
; }
; __device__ __forceinline__ float sum32(float v) { v = dpp_row_sum16(v); v += __shfl_xor(v, 16); return v; }
; __device__ __forceinline__ void seq_item(const Params& p, int item, char* smem, const bool write_o = true) {
;     ...
;       for (int e = 0; e < 16; e++) {
;         const int t = w * 32 + rowmap(e, lane);
;         if (write_o) Om[(size_t)(tok0 + t) * 512 + h * 128 + sl * 32 + r] = f2bf(o[e]);
;         float sq = sum32(o[e] * o[e]);
;         if (r == 0) SSQO[((size_t)(tok0 + t) * 4 + h) * 4 + sl] = sq;
;       }
	v_mov_b32_dpp v94, v94 quad_perm:[1,0,3,2] row_mask:0xf bank_mask:0xf bound_ctrl:1
	v_mov_b32_dpp v95, v95 quad_perm:[1,0,3,2] row_mask:0xf bank_mask:0xf bound_ctrl:1
	v_mov_b32_dpp v96, v96 quad_perm:[1,0,3,2] row_mask:0xf bank_mask:0xf bound_ctrl:1
	v_mov_b32_dpp v97, v97 quad_perm:[1,0,3,2] row_mask:0xf bank_mask:0xf bound_ctrl:1
	v_mov_b32_dpp v98, v98 quad_perm:[1,0,3,2] row_mask:0xf bank_mask:0xf bound_ctrl:1
	v_mov_b32_dpp v99, v99 quad_perm:[1,0,3,2] row_mask:0xf bank_mask:0xf bound_ctrl:1
	v_mov_b32_dpp v100, v100 quad_perm:[1,0,3,2] row_mask:0xf bank_mask:0xf bound_ctrl:1
	v_fmac_f32_e32 v57, v18, v18
	v_fmac_f32_e32 v61, v19, v19
	v_fmac_f32_e32 v87, v20, v20
	v_fmac_f32_e32 v88, v21, v21
	v_fmac_f32_e32 v89, v22, v22
	v_fmac_f32_e32 v90, v23, v23
	v_fmac_f32_e32 v91, v24, v24
	v_fmac_f32_e32 v92, v25, v25
	v_fmac_f32_e32 v93, v26, v26
	v_fmac_f32_e32 v94, v27, v27
	v_fmac_f32_e32 v95, v28, v28
	v_fmac_f32_e32 v96, v29, v29
	v_fmac_f32_e32 v97, v30, v30
	v_fmac_f32_e32 v98, v31, v31
	v_fmac_f32_e32 v99, v32, v32
	v_fmac_f32_e32 v100, v33, v33
	v_add_f32_dpp v57, v57, v57 quad_perm:[2,3,0,1] row_mask:0xf bank_mask:0xf bound_ctrl:1
	v_add_f32_dpp v61, v61, v61 quad_perm:[2,3,0,1] row_mask:0xf bank_mask:0xf bound_ctrl:1
	v_add_f32_dpp v87, v87, v87 quad_perm:[2,3,0,1] row_mask:0xf bank_mask:0xf bound_ctrl:1
	v_add_f32_dpp v88, v88, v88 quad_perm:[2,3,0,1] row_mask:0xf bank_mask:0xf bound_ctrl:1
	v_add_f32_dpp v89, v89, v89 quad_perm:[2,3,0,1] row_mask:0xf bank_mask:0xf bound_ctrl:1
	v_add_f32_dpp v90, v90, v90 quad_perm:[2,3,0,1] row_mask:0xf bank_mask:0xf bound_ctrl:1
	v_add_f32_dpp v91, v91, v91 quad_perm:[2,3,0,1] row_mask:0xf bank_mask:0xf bound_ctrl:1
	v_add_f32_dpp v92, v92, v92 quad_perm:[2,3,0,1] row_mask:0xf bank_mask:0xf bound_ctrl:1
	v_add_f32_dpp v93, v93, v93 quad_perm:[2,3,0,1] row_mask:0xf bank_mask:0xf bound_ctrl:1
	v_add_f32_dpp v94, v94, v94 quad_perm:[2,3,0,1] row_mask:0xf bank_mask:0xf bound_ctrl:1
	v_add_f32_dpp v95, v95, v95 quad_perm:[2,3,0,1] row_mask:0xf bank_mask:0xf bound_ctrl:1
	v_add_f32_dpp v96, v96, v96 quad_perm:[2,3,0,1] row_mask:0xf bank_mask:0xf bound_ctrl:1
	v_add_f32_dpp v97, v97, v97 quad_perm:[2,3,0,1] row_mask:0xf bank_mask:0xf bound_ctrl:1
	v_add_f32_dpp v98, v98, v98 quad_perm:[2,3,0,1] row_mask:0xf bank_mask:0xf bound_ctrl:1
	v_add_f32_dpp v99, v99, v99 quad_perm:[2,3,0,1] row_mask:0xf bank_mask:0xf bound_ctrl:1
	v_add_f32_dpp v100, v100, v100 quad_perm:[2,3,0,1] row_mask:0xf bank_mask:0xf bound_ctrl:1
	v_add_f32_dpp v57, v57, v57 row_half_mirror row_mask:0xf bank_mask:0xf bound_ctrl:1
	v_add_f32_dpp v61, v61, v61 row_half_mirror row_mask:0xf bank_mask:0xf bound_ctrl:1
	v_add_f32_dpp v87, v87, v87 row_half_mirror row_mask:0xf bank_mask:0xf bound_ctrl:1
	v_add_f32_dpp v88, v88, v88 row_half_mirror row_mask:0xf bank_mask:0xf bound_ctrl:1
	v_add_f32_dpp v89, v89, v89 row_half_mirror row_mask:0xf bank_mask:0xf bound_ctrl:1
	v_add_f32_dpp v90, v90, v90 row_half_mirror row_mask:0xf bank_mask:0xf bound_ctrl:1
	v_add_f32_dpp v91, v91, v91 row_half_mirror row_mask:0xf bank_mask:0xf bound_ctrl:1
	v_add_f32_dpp v92, v92, v92 row_half_mirror row_mask:0xf bank_mask:0xf bound_ctrl:1
	v_add_f32_dpp v93, v93, v93 row_half_mirror row_mask:0xf bank_mask:0xf bound_ctrl:1
	v_add_f32_dpp v94, v94, v94 row_half_mirror row_mask:0xf bank_mask:0xf bound_ctrl:1
	v_add_f32_dpp v95, v95, v95 row_half_mirror row_mask:0xf bank_mask:0xf bound_ctrl:1
	v_add_f32_dpp v96, v96, v96 row_half_mirror row_mask:0xf bank_mask:0xf bound_ctrl:1
	v_add_f32_dpp v97, v97, v97 row_half_mirror row_mask:0xf bank_mask:0xf bound_ctrl:1
	v_add_f32_dpp v98, v98, v98 row_half_mirror row_mask:0xf bank_mask:0xf bound_ctrl:1
	v_add_f32_dpp v99, v99, v99 row_half_mirror row_mask:0xf bank_mask:0xf bound_ctrl:1
	v_add_f32_dpp v100, v100, v100 row_half_mirror row_mask:0xf bank_mask:0xf bound_ctrl:1
	v_add_f32_dpp v57, v57, v57 row_mirror row_mask:0xf bank_mask:0xf bound_ctrl:1
	v_add_f32_dpp v61, v61, v61 row_mirror row_mask:0xf bank_mask:0xf bound_ctrl:1
	v_add_f32_dpp v87, v87, v87 row_mirror row_mask:0xf bank_mask:0xf bound_ctrl:1
	v_add_f32_dpp v88, v88, v88 row_mirror row_mask:0xf bank_mask:0xf bound_ctrl:1
	v_add_f32_dpp v89, v89, v89 row_mirror row_mask:0xf bank_mask:0xf bound_ctrl:1
	v_add_f32_dpp v90, v90, v90 row_mirror row_mask:0xf bank_mask:0xf bound_ctrl:1
	v_add_f32_dpp v91, v91, v91 row_mirror row_mask:0xf bank_mask:0xf bound_ctrl:1
	v_add_f32_dpp v92, v92, v92 row_mirror row_mask:0xf bank_mask:0xf bound_ctrl:1
	v_add_f32_dpp v93, v93, v93 row_mirror row_mask:0xf bank_mask:0xf bound_ctrl:1
; __device__ __forceinline__ u16 f2bf(float f) { return (u16)(pack2(f, f) & 0xffffu); }
; __device__ __forceinline__ float sum32(float v) { v = dpp_row_sum16(v); v += __shfl_xor(v, 16); return v; }
; __device__ __forceinline__ int rowmap(int e, int lane) { return (e & 3) + 8 * (e >> 2) + 4 * (lane >> 5); }
; __device__ __forceinline__ void seq_item(const Params& p, int item, char* smem, const bool write_o = true) {
;     ...
;       for (int e = 0; e < 16; e++) {
;         const int t = w * 32 + rowmap(e, lane);
;         if (write_o) Om[(size_t)(tok0 + t) * 512 + h * 128 + sl * 32 + r] = f2bf(o[e]);
;         float sq = sum32(o[e] * o[e]);
;         if (r == 0) SSQO[((size_t)(tok0 + t) * 4 + h) * 4 + sl] = sq;
;       }
	v_add_f32_dpp v94, v94, v94 row_mirror row_mask:0xf bank_mask:0xf bound_ctrl:1
	v_add_f32_dpp v95, v95, v95 row_mirror row_mask:0xf bank_mask:0xf bound_ctrl:1
	v_add_f32_dpp v96, v96, v96 row_mirror row_mask:0xf bank_mask:0xf bound_ctrl:1
	v_add_f32_dpp v97, v97, v97 row_mirror row_mask:0xf bank_mask:0xf bound_ctrl:1
	v_add_f32_dpp v98, v98, v98 row_mirror row_mask:0xf bank_mask:0xf bound_ctrl:1
	v_add_f32_dpp v99, v99, v99 row_mirror row_mask:0xf bank_mask:0xf bound_ctrl:1
	v_add_f32_dpp v100, v100, v100 row_mirror row_mask:0xf bank_mask:0xf bound_ctrl:1
	v_mov_b32_e32 v0, v62
	v_lshlrev_b64 v[78:79], 10, v[0:1]
	v_lshl_add_u64 v[78:79], v[70:71], 0, v[78:79]
	v_cvt_pk_bf16_f32 v18, v18, v18
	v_cvt_pk_bf16_f32 v19, v19, v19
	v_cvt_pk_bf16_f32 v20, v20, v20
	v_cvt_pk_bf16_f32 v21, v21, v21
	global_store_short v[78:79], v18, off
	global_store_short v[78:79], v19, off offset:1024
	global_store_short v[78:79], v20, off offset:2048
	global_store_short v[78:79], v21, off offset:3072
	v_or_b32_e32 v0, 8, v62
	v_lshlrev_b64 v[78:79], 10, v[0:1]
	v_lshl_add_u64 v[78:79], v[70:71], 0, v[78:79]
	v_cvt_pk_bf16_f32 v22, v22, v22
	v_cvt_pk_bf16_f32 v23, v23, v23
	v_cvt_pk_bf16_f32 v24, v24, v24
	v_cvt_pk_bf16_f32 v25, v25, v25
	global_store_short v[78:79], v22, off
	global_store_short v[78:79], v23, off offset:1024
	global_store_short v[78:79], v24, off offset:2048
	global_store_short v[78:79], v25, off offset:3072
	v_or_b32_e32 v0, 16, v62
	v_lshlrev_b64 v[78:79], 10, v[0:1]
	v_lshl_add_u64 v[78:79], v[70:71], 0, v[78:79]
	v_cvt_pk_bf16_f32 v26, v26, v26
	v_cvt_pk_bf16_f32 v27, v27, v27
	v_cvt_pk_bf16_f32 v28, v28, v28
	v_cvt_pk_bf16_f32 v29, v29, v29
	global_store_short v[78:79], v26, off
	global_store_short v[78:79], v27, off offset:1024
	global_store_short v[78:79], v28, off offset:2048
	global_store_short v[78:79], v29, off offset:3072
	v_or_b32_e32 v0, 24, v62
	v_lshlrev_b64 v[78:79], 10, v[0:1]
	v_lshl_add_u64 v[78:79], v[70:71], 0, v[78:79]
	v_cvt_pk_bf16_f32 v30, v30, v30
	v_cvt_pk_bf16_f32 v31, v31, v31
	v_cvt_pk_bf16_f32 v32, v32, v32
	v_cvt_pk_bf16_f32 v33, v33, v33
	global_store_short v[78:79], v30, off
	global_store_short v[78:79], v31, off offset:1024
	global_store_short v[78:79], v32, off offset:2048
	global_store_short v[78:79], v33, off offset:3072
	s_nop 0
	ds_bpermute_b32 v18, v63, v57
	ds_bpermute_b32 v19, v63, v61
	ds_bpermute_b32 v20, v63, v87
	ds_bpermute_b32 v21, v63, v88
	ds_bpermute_b32 v22, v63, v89
	ds_bpermute_b32 v23, v63, v90
	ds_bpermute_b32 v24, v63, v91
	ds_bpermute_b32 v25, v63, v92
	ds_bpermute_b32 v26, v63, v93
	ds_bpermute_b32 v27, v63, v94
	ds_bpermute_b32 v28, v63, v95
	ds_bpermute_b32 v29, v63, v96
	s_waitcnt lgkmcnt(8)
	ds_bpermute_b32 v30, v63, v97
	ds_bpermute_b32 v31, v63, v98
	ds_bpermute_b32 v32, v63, v99
	ds_bpermute_b32 v33, v63, v100
	s_waitcnt lgkmcnt(0)
	v_add_f32_e32 v57, v57, v18
	v_add_f32_e32 v61, v61, v19
	v_add_f32_e32 v87, v87, v20
	v_add_f32_e32 v88, v88, v21
	v_add_f32_e32 v89, v89, v22
	v_add_f32_e32 v90, v90, v23
	v_add_f32_e32 v91, v91, v24
	v_add_f32_e32 v92, v92, v25
	v_add_f32_e32 v93, v93, v26
	v_add_f32_e32 v94, v94, v27
	v_add_f32_e32 v95, v95, v28
	v_add_f32_e32 v96, v96, v29
	v_add_f32_e32 v97, v97, v30
	v_add_f32_e32 v98, v98, v31
	v_add_f32_e32 v99, v99, v32
	v_add_f32_e32 v100, v100, v33
	s_and_b64 exec, exec, s[8:9]
	v_mov_b32_e32 v0, v62
	v_lshlrev_b64 v[78:79], 6, v[0:1]
	v_lshl_add_u64 v[78:79], s[18:19], 0, v[78:79]
	global_store_dword v[78:79], v57, off
	global_store_dword v[78:79], v61, off offset:64
	global_store_dword v[78:79], v87, off offset:128
	global_store_dword v[78:79], v88, off offset:192
	v_or_b32_e32 v0, 8, v62
	v_lshlrev_b64 v[78:79], 6, v[0:1]
	v_lshl_add_u64 v[78:79], s[18:19], 0, v[78:79]
	global_store_dword v[78:79], v89, off
	global_store_dword v[78:79], v90, off offset:64
	global_store_dword v[78:79], v91, off offset:128
	global_store_dword v[78:79], v92, off offset:192
	v_or_b32_e32 v0, 16, v62
	v_lshlrev_b64 v[78:79], 6, v[0:1]
	v_lshl_add_u64 v[78:79], s[18:19], 0, v[78:79]
	global_store_dword v[78:79], v93, off
	global_store_dword v[78:79], v94, off offset:64
	global_store_dword v[78:79], v95, off offset:128
	global_store_dword v[78:79], v96, off offset:192
	v_or_b32_e32 v0, 24, v62
	v_lshlrev_b64 v[78:79], 6, v[0:1]
	v_lshl_add_u64 v[78:79], s[18:19], 0, v[78:79]
	global_store_dword v[78:79], v97, off
	global_store_dword v[78:79], v98, off offset:64
	global_store_dword v[78:79], v99, off offset:128
	global_store_dword v[78:79], v100, off offset:192

; #define GM_LOAD(kt_) { GM_LOAD1(kt_, 0) GM_LOAD1(kt_, 1) GM_LOAD1(kt_, 2) GM_LOAD1(kt_, 3) GM_LOAD1(kt_, 4) GM_LOAD1(kt_, 5) GM_LOAD1(kt_, 6) GM_LOAD1(kt_, 7) }
; template <class AL>
; __device__ __forceinline__ void gemm_mainloop(f32x16 (&acc)[2][2], const AL& al, const u16* __restrict__ Bt, int ldb, int K, char* smem) {
;   const int tid = threadIdx.x, lane = tid & 63, w = tid >> 6;
;   const int wm = w >> 1, wn = w & 1;
;   const int lr = tid >> 4, lk = (tid & 15) * 8;
;   u16* As = (u16*)smem;
;   u16* Bs = As + 2 * 128 * 136;
;   typename AL::Raw ar0, ar1, ar2, ar3, ar4, ar5, ar6, ar7; uint4 br0, br1, br2, br3, br4, br5, br6, br7;
;   const int KT = K >> 7;
;   const int r = lane & 31, hh = (lane >> 5) * 8;
;   __syncthreads();
;   GM_LOAD(0)
;   GM_STORE(0, 0)
;   __syncthreads();
.LBB0_1128:
	s_lshl_b32 s0, s64, 4
	s_and_b32 s0, s0, 0xffffff80
	s_lshl_b32 s1, s64, 7
	s_and_b32 s65, s1, 0x380
	s_ashr_i32 s1, s0, 31
	s_xor_b64 s[18:19], s[16:17], -1
	s_and_b32 s66, s8, 1
	s_lshl_b64 s[20:21], s[0:1], 10
	s_lshl_b64 s[22:23], s[0:1], 11
	s_add_u32 s24, s38, s22
	s_addc_u32 s25, s39, s23
	s_lshl_b32 s8, s66, 21
	s_lshl_b32 s26, s65, 11
	s_or_b32 s8, s26, s8
	s_add_u32 s26, s80, s8
	s_addc_u32 s27, s81, 0
	s_waitcnt lgkmcnt(0)
	v_accvgpr_read_b32 v2, a104
	v_accvgpr_read_b32 v6, a106
	v_accvgpr_read_b32 v10, a108
	v_accvgpr_read_b32 v14, a110
	v_accvgpr_read_b32 v18, a112
	v_accvgpr_read_b32 v22, a114
	v_accvgpr_read_b32 v26, a116
	v_accvgpr_read_b32 v30, a118
	s_add_u32 s26, s26, 0x800000
	v_accvgpr_read_b32 v3, a105
	v_accvgpr_read_b32 v7, a107
	v_accvgpr_read_b32 v11, a109
	v_accvgpr_read_b32 v15, a111
	v_accvgpr_read_b32 v19, a113
	v_accvgpr_read_b32 v23, a115
	v_accvgpr_read_b32 v27, a117
	v_accvgpr_read_b32 v31, a119
	s_addc_u32 s27, s27, 0
	v_lshl_add_u64 v[0:1], s[24:25], 0, v[2:3]
	v_lshl_add_u64 v[4:5], s[24:25], 0, v[6:7]
	v_lshl_add_u64 v[8:9], s[24:25], 0, v[10:11]
	v_lshl_add_u64 v[12:13], s[24:25], 0, v[14:15]
	v_lshl_add_u64 v[16:17], s[24:25], 0, v[18:19]
	v_lshl_add_u64 v[20:21], s[24:25], 0, v[22:23]
	v_lshl_add_u64 v[24:25], s[24:25], 0, v[26:27]
	v_lshl_add_u64 v[28:29], s[24:25], 0, v[30:31]
	v_lshl_add_u64 v[32:33], v[0:1], 0, v[76:77]
	v_lshl_add_u64 v[0:1], s[26:27], 0, v[2:3]
	v_lshl_add_u64 v[36:37], v[4:5], 0, v[76:77]
	v_lshl_add_u64 v[4:5], s[26:27], 0, v[6:7]
	v_lshl_add_u64 v[38:39], v[8:9], 0, v[76:77]
	v_lshl_add_u64 v[8:9], s[26:27], 0, v[10:11]
	v_lshl_add_u64 v[40:41], v[12:13], 0, v[76:77]
	v_lshl_add_u64 v[12:13], s[26:27], 0, v[14:15]
	v_lshl_add_u64 v[42:43], v[16:17], 0, v[76:77]
	v_lshl_add_u64 v[16:17], s[26:27], 0, v[18:19]
	v_lshl_add_u64 v[44:45], v[20:21], 0, v[76:77]
	v_lshl_add_u64 v[20:21], s[26:27], 0, v[22:23]
	v_lshl_add_u64 v[46:47], v[24:25], 0, v[76:77]
	v_lshl_add_u64 v[24:25], s[26:27], 0, v[26:27]
	v_lshl_add_u64 v[48:49], v[28:29], 0, v[76:77]
	v_lshl_add_u64 v[28:29], s[26:27], 0, v[30:31]
	v_lshl_add_u64 v[0:1], v[0:1], 0, v[76:77]
	v_lshl_add_u64 v[4:5], v[4:5], 0, v[76:77]
	v_lshl_add_u64 v[8:9], v[8:9], 0, v[76:77]
	v_lshl_add_u64 v[12:13], v[12:13], 0, v[76:77]
	v_lshl_add_u64 v[16:17], v[16:17], 0, v[76:77]
	v_lshl_add_u64 v[20:21], v[20:21], 0, v[76:77]
	v_lshl_add_u64 v[24:25], v[24:25], 0, v[76:77]
	v_lshl_add_u64 v[28:29], v[28:29], 0, v[76:77]
	s_barrier
	global_load_dwordx4 v[0:3], v[0:1], off
	v_accvgpr_read_b32 v109, a103
	global_load_dwordx4 v[4:7], v[4:5], off
	v_accvgpr_write_b32 a15, 0
	global_load_dwordx4 v[8:11], v[8:9], off
	v_accvgpr_write_b32 a14, 0
	global_load_dwordx4 v[12:15], v[12:13], off
	v_accvgpr_write_b32 a13, 0
	global_load_dwordx4 v[16:19], v[16:17], off
	v_accvgpr_write_b32 a12, 0
	global_load_dwordx4 v[20:23], v[20:21], off
	v_accvgpr_write_b32 a11, 0
	global_load_dwordx4 v[24:27], v[24:25], off
	s_nop 0
	global_load_dwordx4 v[28:31], v[28:29], off
	s_nop 0
	global_load_dwordx4 v[32:35], v[32:33], off
	global_load_dwordx4 a[196:199], v[36:37], off
	global_load_dwordx4 a[200:203], v[38:39], off
	global_load_dwordx4 a[204:207], v[40:41], off
	global_load_dwordx4 a[208:211], v[42:43], off
	global_load_dwordx4 a[212:215], v[44:45], off
	global_load_dwordx4 a[216:219], v[46:47], off
	global_load_dwordx4 a[220:223], v[48:49], off
	v_accvgpr_write_b32 a10, 0
	v_accvgpr_write_b32 a9, 0
	v_accvgpr_write_b32 a8, 0
	v_accvgpr_write_b32 a7, 0
	v_accvgpr_write_b32 a6, 0
	v_accvgpr_write_b32 a5, 0
	v_accvgpr_write_b32 a4, 0
	v_accvgpr_write_b32 a3, 0
	v_accvgpr_write_b32 a2, 0
	v_accvgpr_write_b32 a1, 0
	s_waitcnt vmcnt(0)
	ds_write_b128 v134, v[32:35]
	ds_write_b128 v136, v[0:3]
	v_accvgpr_write_b32 a0, 0
	v_accvgpr_write_b32 a47, 0
	v_accvgpr_write_b32 a46, 0
	v_accvgpr_write_b32 a45, 0
	v_accvgpr_write_b32 a44, 0
	v_accvgpr_write_b32 a43, 0
	v_accvgpr_write_b32 a42, 0
	v_accvgpr_write_b32 a41, 0
	v_accvgpr_write_b32 a40, 0
	v_accvgpr_write_b32 a39, 0
	ds_write_b128 v134, a[196:199] offset:4352
	ds_write_b128 v138, v[4:7]
	v_accvgpr_write_b32 a38, 0
	v_accvgpr_write_b32 a37, 0
	v_accvgpr_write_b32 a36, 0
	v_accvgpr_write_b32 a35, 0
	v_accvgpr_write_b32 a34, 0
	v_accvgpr_write_b32 a33, 0
	v_accvgpr_write_b32 a32, 0
	v_accvgpr_write_b32 a63, 0
	v_accvgpr_write_b32 a62, 0
	v_accvgpr_write_b32 a61, 0
	ds_write_b128 v134, a[200:203] offset:8704
	ds_write_b128 v139, v[8:11]
	v_accvgpr_write_b32 a60, 0
	v_accvgpr_write_b32 a59, 0
	v_accvgpr_write_b32 a58, 0
	v_accvgpr_write_b32 a57, 0
	v_accvgpr_write_b32 a56, 0
	v_accvgpr_write_b32 a55, 0
	v_accvgpr_write_b32 a54, 0
	v_accvgpr_write_b32 a53, 0
	v_accvgpr_write_b32 a52, 0
	v_accvgpr_write_b32 a51, 0
	ds_write_b128 v134, a[204:207] offset:13056
	ds_write_b128 v176, v[12:15]
	v_accvgpr_write_b32 a50, 0
	v_accvgpr_write_b32 a49, 0
	v_accvgpr_write_b32 a48, 0
	v_accvgpr_write_b32 a31, 0
	v_accvgpr_write_b32 a30, 0
	v_accvgpr_write_b32 a29, 0
	v_accvgpr_write_b32 a28, 0
	v_accvgpr_write_b32 a27, 0
	v_accvgpr_write_b32 a26, 0
	v_accvgpr_write_b32 a25, 0
	ds_write_b128 v134, a[208:211] offset:17408
	ds_write_b128 v177, v[16:19]
	v_accvgpr_write_b32 a24, 0
	v_accvgpr_write_b32 a23, 0
	v_accvgpr_write_b32 a22, 0
	v_accvgpr_write_b32 a21, 0
	v_accvgpr_write_b32 a20, 0
	v_accvgpr_write_b32 a19, 0
	v_accvgpr_write_b32 a18, 0
	v_accvgpr_write_b32 a17, 0
	v_accvgpr_write_b32 a16, 0
	s_mov_b32 s67, 0
	ds_write_b128 v134, a[212:215] offset:21760
	ds_write_b128 v198, v[20:23]
	v_accvgpr_read_b32 v108, a102
	ds_write_b128 v134, a[216:219] offset:26112
	ds_write_b128 v200, v[24:27]
	ds_write_b128 v134, a[220:223] offset:30464
	ds_write_b128 v201, v[28:31]
	s_waitcnt lgkmcnt(0)
	s_barrier
	s_branch .LBB0_1130
